# v11 + removed the no-op Newton refinement after the constant reciprocals in the unit scheduler (71 sites)
# speedup vs baseline: 1.0016x; 1.0016x over previous
;     __device__ __forceinline__ bool next(int i, Unit& u) const {
;     ...
;         const long L = (long)i * G + c; if (L >= nwg) return false;
;         int wgid = (int)L; { const int q = nwg / NXCD, r = nwg % NXCD, xcd = wgid % NXCD, off = wgid / NXCD; wgid = (xcd < r ? xcd * (q + 1) : r * (q + 1) + (xcd - r) * q) + off; }
;         if (rev) wgid = nwg - 1 - wgid;
;         const int per = nM * nN, z = wgid / per, rem = wgid - z * per;
;         const int nig = WGM * nN, gid = rem / nig, fm = gid * WGM, gsz = (nM - fm) < WGM ? (nM - fm) : WGM, ri = rem - gid * nig;
;         u.pm = fm + (ri % gsz); u.pn = ri / gsz; u.z1 = z / Z2; u.z2 = z - u.z1 * Z2; return true;
; template <class Epi>
; __device__ __forceinline__ void gemm_phase(PG8_LAS unsigned char* lds, PG8_LAS unsigned char* xl, const Gemm g, const Sched& S, const Epi& E, const int wid) {
;     ...
;     for (int i = 0; i < 2; ++i) { int R, C; stage_rc(tid * 16 + i * 8192, R, C); const int Rb = Epi::PERM ? ((R & ~31) + perm32(R & 31)) : R;
;         const int Ra = Epi::PERM ? ((R & ~63) + 4 * (R & 15) + ((R >> 4) & 3)) : R;
;         voffA[i] = (unsigned)(Ra * g.lda + C) * 2u; voffB[i] = (unsigned)(Rb * g.ldb + C) * 2u; }
;     const size_t kstep = (size_t)(BK * 2);
;     const size_t hstepA = (size_t)HALF * g.lda * 2, hstepB = (size_t)HALF * g.ldb * 2;
;     const unsigned ldsw = (unsigned)wid * 1024u;
;     const int aoff = lds_byte(wr * 64 + fr, fq * 8), boff = lds_byte(wc * 32 + fr, fq * 8);
;     ...
;     Unit cur, nxt; int ui = 0;
;     if (!S.next(0, cur)) return;
;     Acc acc;
; #pragma unroll
;     for (int a = 0; a < 2; ++a)
; #pragma unroll
;         for (int b = 0; b < 2; ++b)
; #pragma unroll
;             for (int m = 0; m < 4; ++m)
; #pragma unroll
;                 for (int n = 0; n < 2; ++n) acc[a][b][m][n] = (f32x4){0.f, 0.f, 0.f, 0.f};
;     bf16x8 At[4][2], B0[2][2], B1[2][2];
;     float prc[8];
; #pragma unroll
;     for (int k = 0; k < 8; ++k) prc[k] = 1.0f;
;     if constexpr (Epi::PRE) { const float* pb = E.pre_base(cur) + wr * 64 + 4 * fr;
; #pragma unroll
;         for (int k = 0; k < 8; ++k) prc[k] = pb[(k >> 2) * HALF + (k & 3)]; }
;     const char* cA = a_tile(g, cur); const char* cB = b_tile(g, cur);
;     PG8_STAGE(PG8_SB(0, 0), cB, voffB); PG8_STAGE(PG8_SB(0, 1), cB + hstepB, voffB); PG8_STAGE(PG8_SA(0, 0), cA, voffA); PG8_STAGE(PG8_SA(0, 1), cA + hstepA, voffA);
;     if (wr == 1) PG8_BAR;
.LBB0_211:
	v_readlane_b32 s8, v253, 0
	v_readlane_b32 s9, v253, 1
	s_mov_b32 s0, s36
	s_waitcnt lgkmcnt(0)
	s_barrier
	s_load_dwordx4 s[44:47], s[8:9], 0xd0
	v_readlane_b32 s4, v254, 16
	v_readlane_b32 s1, v254, 13
	v_readlane_b32 s5, v254, 17
	s_add_i32 s1, s0, s1
	s_mov_b32 s8, 20
	v_cndmask_b32_e64 v0, 0, 1, s[4:5]
	s_mov_b32 s10, 1
	s_mov_b32 s9, 16
	s_cmpk_gt_i32 s1, 0x13f
	v_cmp_ne_u32_e64 s[38:39], 1, v0
	v_mbcnt_lo_u32_b32 v8, -1, 0
	v_mbcnt_hi_u32_b32 v8, -1, v8
	s_cbranch_scc1 .LBB0_227
	v_lshlrev_b32_e32 v10, 4, v8
	v_add_u32_e32 v0, s29, v10
	v_add_u32_e32 v1, 0x2000, v0
	v_ashrrev_i32_e32 v2, 31, v1
	v_lshrrev_b32_e32 v2, 22, v2
	v_add_u32_e32 v2, v1, v2
	v_ashrrev_i32_e32 v9, 10, v2
	v_mul_i32_i24_e32 v2, 0x400, v9
	v_sub_u32_e32 v1, v1, v2
	v_lshrrev_b32_e32 v2, 4, v1
	v_bitop3_b32 v1, v2, v1, 32 bitop3:0x6c
	v_ashrrev_i32_e32 v2, 31, v1
	v_lshrrev_b32_e32 v2, 26, v2
	v_add_u32_e32 v2, v1, v2
	v_ashrrev_i32_e32 v3, 6, v2
	v_lshlrev_b32_e32 v4, 3, v9
	v_and_b32_e32 v2, 0xffc0, v2
	v_and_b32_e32 v4, -16, v4
	v_sub_u32_e32 v1, v1, v2
	v_add_u32_e32 v4, v3, v4
	v_lshrrev_b16_e32 v2, 7, v1
	v_and_b32_e32 v3, 3, v3
	s_mov_b32 s4, 0xfffe0
	v_lshrrev_b32_e32 v5, 2, v4
	v_lshlrev_b32_e32 v6, 1, v4
	v_and_b32_e32 v2, 1, v2
	v_and_or_b32 v3, v4, s4, v3
	v_and_b32_e32 v5, 4, v5
	v_and_b32_e32 v6, 24, v6
	v_add_u16_e32 v1, v1, v2
	v_or3_b32 v3, v3, v5, v6
	v_lshlrev_b32_e32 v5, 5, v9
	v_ashrrev_i16_sdwa v1, v244, sext(v1) dst_sel:DWORD dst_unused:UNUSED_PAD src0_sel:DWORD src1_sel:BYTE_0
	v_lshlrev_b32_e32 v2, 2, v4
	v_and_b32_e32 v5, 32, v5
	v_bfe_i32 v11, v1, 0, 16
	v_and_b32_e32 v12, 0xfffc0, v4
	v_and_b32_e32 v13, 60, v2
	v_bfe_u32 v14, v4, 4, 2
	v_add_lshl_u32 v1, v5, v11, 1
	v_or3_b32 v2, v12, v13, v14
	v_lshl_add_u32 v128, v3, 12, v1
	v_lshl_add_u32 v130, v2, 12, v1
	v_ashrrev_i32_e32 v1, 31, v0
	v_lshrrev_b32_e32 v1, 22, v1
	s_waitcnt lgkmcnt(0)
	s_add_u32 s60, s46, 0x14c00000
	v_add_u32_e32 v1, v0, v1
	s_addc_u32 s61, s47, 0
	v_ashrrev_i32_e32 v15, 10, v1
	s_add_u32 s62, s46, 0x5000000
	v_mul_i32_i24_e32 v1, 0x400, v15
	s_addc_u32 s66, s47, 0
	v_sub_u32_e32 v0, v0, v1
	s_ashr_i32 s67, s1, 31
	v_lshrrev_b32_e32 v1, 4, v0
	s_lshr_b32 s10, s67, 29
	v_bitop3_b32 v0, v1, v0, 32 bitop3:0x6c
	s_add_i32 s10, s1, s10
	v_ashrrev_i32_e32 v1, 31, v0
	s_ashr_i32 s11, s10, 3
	s_and_b32 s10, s10, -8
	v_lshrrev_b32_e32 v1, 26, v1
	s_sub_i32 s10, s1, s10
	v_add_u32_e32 v1, v0, v1
	s_cmp_lt_i32 s10, 0
	s_mul_i32 s13, s8, s9
	v_ashrrev_i32_e32 v2, 6, v1
	v_and_b32_e32 v1, 0xc0, v1
	s_cselect_b32 s12, 41, 40
	s_abs_i32 s13, s13
	v_sub_u32_e32 v0, v0, v1
	s_mul_i32 s10, s10, s12
	s_sub_i32 s12, 0, s13
	s_add_i32 s10, s10, s11
	s_ashr_i32 s11, s10, 31
	s_abs_i32 s10, s10
	v_lshlrev_b32_e32 v3, 3, v15
	v_and_b32_e32 v3, -16, v3
	v_add_u32_e32 v3, v2, v3
	v_and_b32_e32 v2, 3, v2
	s_mov_b32 s20, 0xcccccc
	s_mul_hi_u32 s12, s10, s20
	s_mul_i32 s12, s12, s13
	s_sub_i32 s10, s10, s12
	s_sub_i32 s12, s10, s13
	s_cmp_ge_u32 s10, s13
	s_cselect_b32 s10, s12, s10
	s_sub_i32 s12, s10, s13
	s_cmp_ge_u32 s10, s13
	s_cselect_b32 s10, s12, s10
	s_lshl_b32 s9, s9, 2
	s_abs_i32 s12, s9
	s_sub_i32 s20, 0, s12
	s_xor_b32 s10, s10, s11
	s_sub_i32 s10, s10, s11
	s_abs_i32 s13, s10
	s_xor_b32 s11, s10, s9
	s_ashr_i32 s11, s11, 31
	v_lshrrev_b32_e32 v4, 2, v3
	v_lshlrev_b32_e32 v5, 1, v3
	v_and_or_b32 v2, v3, s4, v2
	s_mov_b32 s21, 0x4000000
	s_mul_hi_u32 s20, s13, s21
	s_mul_i32 s21, s20, s12
	s_sub_i32 s13, s13, s21
	s_add_i32 s21, s20, 1
	s_sub_i32 s30, s13, s12
	s_cmp_ge_u32 s13, s12
	s_cselect_b32 s20, s21, s20
	s_cselect_b32 s13, s30, s13
	s_add_i32 s21, s20, 1
	s_cmp_ge_u32 s13, s12
	s_cselect_b32 s12, s21, s20
	s_xor_b32 s12, s12, s11
	s_sub_i32 s11, s12, s11
	s_lshl_b32 s12, s11, 2
	v_and_b32_e32 v4, 4, v4
	v_and_b32_e32 v5, 24, v5
	s_sub_i32 s8, s8, s12
	v_or3_b32 v2, v2, v4, v5
	v_lshlrev_b32_e32 v4, 5, v15
	v_ashrrev_i16_sdwa v0, v244, sext(v0) dst_sel:DWORD dst_unused:UNUSED_PAD src0_sel:DWORD src1_sel:BYTE_0
	s_min_i32 s8, s8, 4
	v_and_b32_e32 v4, 32, v4
	v_bfe_i32 v16, v0, 0, 16
	s_abs_i32 s13, s8
	v_add_lshl_u32 v0, v4, v16, 1
	v_cvt_f32_u32_e32 v1, s13
	v_lshl_add_u32 v132, v2, 12, v0
	v_lshlrev_b32_e32 v2, 2, v3
	v_and_b32_e32 v17, 0xfffc0, v3
	v_and_b32_e32 v18, 60, v2
	v_bfe_u32 v19, v3, 4, 2
	v_or3_b32 v2, v17, v18, v19
	v_lshl_add_u32 v134, v2, 12, v0
	v_rcp_iflag_f32_e32 v0, v1
	s_sub_i32 s20, 0, s13
	s_mul_i32 s11, s11, s9
	s_sub_i32 s9, s10, s11
	v_mul_f32_e32 v0, 0x4f7ffffe, v0
	v_cvt_u32_f32_e32 v0, v0
	s_abs_i32 s11, s9
	s_xor_b32 s10, s9, s8
	s_ashr_i32 s10, s10, 31
	v_readfirstlane_b32 s21, v0
	s_mul_i32 s20, s20, s21
	s_mul_hi_u32 s20, s21, s20
	s_add_i32 s21, s21, s20
	s_mul_hi_u32 s20, s11, s21
	s_mul_i32 s21, s20, s13
	s_sub_i32 s11, s11, s21
	s_add_i32 s21, s20, 1
	s_sub_i32 s30, s11, s13
	s_cmp_ge_u32 s11, s13
	s_cselect_b32 s20, s21, s20
	s_cselect_b32 s11, s30, s11
	s_add_i32 s21, s20, 1
	s_cmp_ge_u32 s11, s13
	s_cselect_b32 s11, s21, s20
	s_xor_b32 s11, s11, s10
	s_sub_i32 s36, s11, s10
	s_mul_i32 s8, s36, s8
	s_sub_i32 s8, s9, s8
	s_ashr_i32 s37, s36, 31
	s_add_i32 s42, s12, s8
	s_lshl_b64 s[8:9], s[36:37], 20
	s_add_u32 s52, s62, s8
	s_addc_u32 s53, s66, s9
	s_add_i32 s37, s29, 0
	s_add_i32 m0, s37, 0x10000
	s_ashr_i32 s43, s42, 31
	global_load_lds_dwordx4 v132, s[52:53]
	s_add_i32 m0, s37, 0x12000
	s_add_u32 s8, s52, 0x80000
	global_load_lds_dwordx4 v128, s[52:53]
	s_addc_u32 s9, s53, 0
	s_add_i32 m0, s37, 0x14000
	v_mov_b32_e32 v133, v193
	global_load_lds_dwordx4 v132, s[8:9]
	s_add_i32 m0, s37, 0x16000
	v_mov_b32_e32 v129, v193
	global_load_lds_dwordx4 v128, s[8:9]
	s_lshl_b64 s[8:9], s[42:43], 20
	s_add_u32 s50, s60, s8
	s_addc_u32 s51, s61, s9
	s_add_i32 s68, s37, 0x2000
	s_mov_b32 m0, s37
	s_add_u32 s8, s50, 0x80000
	global_load_lds_dwordx4 v134, s[50:51]
	s_mov_b32 m0, s68
	s_addc_u32 s9, s51, 0
	s_add_i32 s69, s37, 0x4000
	global_load_lds_dwordx4 v130, s[50:51]
	s_mov_b32 m0, s69
	s_add_i32 s70, s37, 0x6000
	global_load_lds_dwordx4 v134, s[8:9]
	s_mov_b32 m0, s70
	v_mov_b32_e32 v135, v193
	global_load_lds_dwordx4 v130, s[8:9]
	v_mov_b32_e32 v131, v193
	v_lshl_add_u64 v[6:7], s[52:53], 0, v[132:133]
	v_lshl_add_u64 v[4:5], s[52:53], 0, v[128:129]
	v_lshl_add_u64 v[2:3], s[50:51], 0, v[134:135]
	s_and_b64 vcc, exec, s[38:39]
	v_lshl_add_u64 v[0:1], s[50:51], 0, v[130:131]
	s_cbranch_vccnz .LBB0_214
	s_barrier

;     __device__ __forceinline__ bool next(int i, Unit& u) const {
;         int nM = this->nM, nN = this->nN, Z2 = this->Z2; asm volatile("" : "+s"(nM), "+s"(nN), "+s"(Z2));
;         const long L = (long)i * G + c; if (L >= nwg) return false;
;         int wgid = (int)L; { const int q = nwg / NXCD, r = nwg % NXCD, xcd = wgid % NXCD, off = wgid / NXCD; wgid = (xcd < r ? xcd * (q + 1) : r * (q + 1) + (xcd - r) * q) + off; }
;         if (rev) wgid = nwg - 1 - wgid;
;         const int per = nM * nN, z = wgid / per, rem = wgid - z * per;
;         const int nig = WGM * nN, gid = rem / nig, fm = gid * WGM, gsz = (nM - fm) < WGM ? (nM - fm) : WGM, ri = rem - gid * nig;
;         u.pm = fm + (ri % gsz); u.pn = ri / gsz; u.z1 = z / Z2; u.z2 = z - u.z1 * Z2; return true;
; template <class Epi>
; __device__ __forceinline__ void gemm_phase(PG8_LAS unsigned char* lds, PG8_LAS unsigned char* xl, const Gemm g, const Sched& S, const Epi& E, const int wid) {
;     ...
;         const bool has_next = S.next(ui + 1, nxt);
.LBB0_217:
	s_mov_b32 s8, 20
	s_mov_b32 s10, 1
	s_mov_b32 s9, 16
	s_add_i32 s89, s89, 1
	s_mul_i32 s10, s89, s88
	s_mul_hi_u32 s11, s89, s0
	s_add_i32 s11, s11, s10
	s_mul_i32 s10, s89, s0
	s_add_u32 s10, s10, s1
	s_addc_u32 s11, s11, s67
	v_mov_b64_e32 v[0:1], 0x140
	v_cmp_lt_i64_e64 s[40:41], s[10:11], v[0:1]
	v_mov_b64_e32 v[0:1], 0x13f
	v_cmp_gt_i64_e32 vcc, s[10:11], v[0:1]
	s_cbranch_vccnz .LBB0_219
	s_ashr_i32 s11, s10, 31
	s_lshr_b32 s11, s11, 29
	s_add_i32 s11, s10, s11
	s_ashr_i32 s12, s11, 3
	s_and_b32 s11, s11, -8
	s_sub_i32 s10, s10, s11
	s_cmp_lt_i32 s10, 0
	s_mul_i32 s13, s8, s9
	s_cselect_b32 s11, 41, 40
	s_abs_i32 s13, s13
	s_mul_i32 s10, s10, s11
	s_sub_i32 s11, 0, s13
	s_add_i32 s10, s10, s12
	s_ashr_i32 s12, s10, 31
	s_abs_i32 s10, s10
	s_mov_b32 s20, 0xcccccc
	s_mul_hi_u32 s11, s10, s20
	s_mul_i32 s11, s11, s13
	s_sub_i32 s10, s10, s11
	s_sub_i32 s11, s10, s13
	s_cmp_ge_u32 s10, s13
	s_cselect_b32 s10, s11, s10
	s_sub_i32 s11, s10, s13
	s_cmp_ge_u32 s10, s13
	s_cselect_b32 s10, s11, s10
	s_lshl_b32 s9, s9, 2
	s_abs_i32 s11, s9
	s_xor_b32 s10, s10, s12
	s_sub_i32 s10, s10, s12
	s_sub_i32 s12, 0, s11
	s_abs_i32 s20, s10
	s_xor_b32 s13, s10, s9
	s_ashr_i32 s13, s13, 31
	s_mov_b32 s21, 0x4000000
	s_mul_hi_u32 s12, s20, s21
	s_mul_i32 s21, s12, s11
	s_sub_i32 s20, s20, s21
	s_add_i32 s30, s12, 1
	s_sub_i32 s21, s20, s11
	s_cmp_ge_u32 s20, s11
	s_cselect_b32 s12, s30, s12
	s_cselect_b32 s20, s21, s20
	s_add_i32 s21, s12, 1
	s_cmp_ge_u32 s20, s11
	s_cselect_b32 s11, s21, s12
	s_xor_b32 s11, s11, s13
	s_sub_i32 s11, s11, s13
	s_lshl_b32 s13, s11, 2
	s_sub_i32 s8, s8, s13
	s_min_i32 s8, s8, 4
	s_abs_i32 s12, s8
	s_sub_i32 s20, 0, s12
	s_mul_i32 s11, s11, s9
	s_sub_i32 s9, s10, s11
	s_abs_i32 s10, s9
	s_xor_b32 s11, s9, s8
	s_ashr_i32 s11, s11, 31
	s_mov_b32 s21, 0x40000000
	s_mul_hi_u32 s20, s10, s21
	s_mul_i32 s21, s20, s12
	s_sub_i32 s10, s10, s21
	s_add_i32 s30, s20, 1
	s_sub_i32 s21, s10, s12
	s_cmp_ge_u32 s10, s12
	s_cselect_b32 s20, s30, s20
	s_cselect_b32 s10, s21, s10
	s_add_i32 s21, s20, 1
	s_cmp_ge_u32 s10, s12
	s_cselect_b32 s10, s21, s20
	s_xor_b32 s10, s10, s11
	s_sub_i32 s12, s10, s11
	s_mul_i32 s8, s12, s8
	s_sub_i32 s8, s9, s8
	s_add_i32 s20, s13, s8

;     __device__ __forceinline__ bool next(int i, Unit& u) const {
;         int nM = this->nM, nN = this->nN, Z2 = this->Z2; asm volatile("" : "+s"(nM), "+s"(nN), "+s"(Z2));
;         const long L = (long)i * G + c; if (L >= nwg) return false;
;         int wgid = (int)L; { const int q = nwg / NXCD, r = nwg % NXCD, xcd = wgid % NXCD, off = wgid / NXCD; wgid = (xcd < r ? xcd * (q + 1) : r * (q + 1) + (xcd - r) * q) + off; }
;         if (rev) wgid = nwg - 1 - wgid;
;         const int per = nM * nN, z = wgid / per, rem = wgid - z * per;
;         const int nig = WGM * nN, gid = rem / nig, fm = gid * WGM, gsz = (nM - fm) < WGM ? (nM - fm) : WGM, ri = rem - gid * nig;
;         u.pm = fm + (ri % gsz); u.pn = ri / gsz; u.z1 = z / Z2; u.z2 = z - u.z1 * Z2; return true;
; template <class Epi>
; __device__ __forceinline__ void gemm_phase(PG8_LAS unsigned char* lds, PG8_LAS unsigned char* xl, const Gemm g, const Sched& S, const Epi& E, const int wid) {
;     ...
;     if (!S.next(0, cur)) return;
.LBB0_227:
	v_readlane_b32 s4, v254, 20
	v_readlane_b32 s5, v254, 21
	s_mov_b32 s9, 1
	s_movk_i32 s1, 0xa0
	v_cndmask_b32_e64 v0, 0, 1, s[4:5]
	s_mov_b32 s8, 28
	v_cmp_ne_u32_e64 s[40:41], 1, v0
	s_andn2_b64 vcc, exec, s[4:5]
	v_mbcnt_lo_u32_b32 v8, -1, 0
	v_mbcnt_hi_u32_b32 v8, -1, v8
	s_cbranch_vccnz .LBB0_229
	s_mul_i32 s9, s1, s8
	s_abs_i32 s9, s9
	s_sub_i32 s10, 0, s9
	v_readlane_b32 s4, v254, 49
	s_nop 0
	s_mov_b32 s11, 0xea0ea
	s_mul_hi_u32 s10, s4, s11
	s_mul_i32 s10, s10, s9
	s_sub_i32 s10, s4, s10
	s_sub_i32 s11, s10, s9
	s_cmp_ge_u32 s10, s9
	s_cselect_b32 s10, s11, s10
	s_sub_i32 s11, s10, s9
	s_cmp_ge_u32 s10, s9
	s_cselect_b32 s9, s11, s10
	s_lshl_b32 s8, s8, 2
	s_abs_i32 s10, s8
	v_readlane_b32 s4, v254, 48
	s_sub_i32 s11, 0, s10
	s_xor_b32 s9, s9, s4
	s_sub_i32 s9, s9, s4
	s_abs_i32 s13, s9
	s_xor_b32 s12, s9, s8
	s_ashr_i32 s12, s12, 31
	s_mov_b32 s20, 0x2492492
	s_mul_hi_u32 s11, s13, s20
	s_mul_i32 s20, s11, s10
	s_sub_i32 s13, s13, s20
	s_add_i32 s21, s11, 1
	s_sub_i32 s20, s13, s10
	s_cmp_ge_u32 s13, s10
	s_cselect_b32 s11, s21, s11
	s_cselect_b32 s13, s20, s13
	s_add_i32 s20, s11, 1
	s_cmp_ge_u32 s13, s10
	s_cselect_b32 s10, s20, s11
	s_xor_b32 s10, s10, s12
	s_sub_i32 s10, s10, s12
	s_lshl_b32 s11, s10, 2
	s_sub_i32 s1, s1, s11
	s_min_i32 s1, s1, 4
	s_abs_i32 s12, s1
	s_sub_i32 s13, 0, s12
	s_mul_i32 s10, s10, s8
	s_sub_i32 s8, s9, s10
	s_abs_i32 s9, s8
	s_xor_b32 s10, s8, s1
	s_ashr_i32 s10, s10, 31
	s_mov_b32 s20, 0x40000000
	s_mul_hi_u32 s13, s9, s20
	s_mul_i32 s20, s13, s12
	s_sub_i32 s9, s9, s20
	s_add_i32 s21, s13, 1
	s_sub_i32 s20, s9, s12
	s_cmp_ge_u32 s9, s12
	s_cselect_b32 s13, s21, s13
	s_cselect_b32 s9, s20, s9
	s_add_i32 s20, s13, 1
	s_cmp_ge_u32 s9, s12
	s_cselect_b32 s9, s20, s13
	s_xor_b32 s9, s9, s10
	s_sub_i32 s12, s9, s10
	s_mul_i32 s1, s12, s1
	s_sub_i32 s1, s8, s1
	s_add_i32 s48, s11, s1

;     __device__ __forceinline__ bool next(int i, Unit& u) const {
;         int nM = this->nM, nN = this->nN, Z2 = this->Z2; asm volatile("" : "+s"(nM), "+s"(nN), "+s"(Z2));
;         const long L = (long)i * G + c; if (L >= nwg) return false;
;         int wgid = (int)L; { const int q = nwg / NXCD, r = nwg % NXCD, xcd = wgid % NXCD, off = wgid / NXCD; wgid = (xcd < r ? xcd * (q + 1) : r * (q + 1) + (xcd - r) * q) + off; }
;         if (rev) wgid = nwg - 1 - wgid;
;         const int per = nM * nN, z = wgid / per, rem = wgid - z * per;
;         const int nig = WGM * nN, gid = rem / nig, fm = gid * WGM, gsz = (nM - fm) < WGM ? (nM - fm) : WGM, ri = rem - gid * nig;
;         u.pm = fm + (ri % gsz); u.pn = ri / gsz; u.z1 = z / Z2; u.z2 = z - u.z1 * Z2; return true;
; template <class Epi>
; __device__ __forceinline__ void gemm_phase(PG8_LAS unsigned char* lds, PG8_LAS unsigned char* xl, const Gemm g, const Sched& S, const Epi& E, const int wid) {
;     ...
;         const bool has_next = S.next(ui + 1, nxt);
.LBB0_235:
	s_mov_b32 s10, 1
	s_movk_i32 s8, 0xa0
	s_mov_b32 s9, 28
	s_add_i32 s96, s96, 1
	s_mul_i32 s10, s96, s95
	s_mul_hi_u32 s11, s96, s0
	s_add_i32 s11, s11, s10
	s_mul_i32 s10, s96, s0
	s_add_u32 s10, s10, s2
	s_addc_u32 s11, s11, s33
	v_mov_b64_e32 v[0:1], 0x1180
	v_cmp_lt_i64_e64 s[40:41], s[10:11], v[0:1]
	v_mov_b64_e32 v[0:1], 0x117f
	v_cmp_gt_i64_e64 s[42:43], s[10:11], v[0:1]
	s_and_b64 vcc, exec, s[42:43]
	s_cbranch_vccnz .LBB0_237
	s_ashr_i32 s11, s10, 31
	s_lshr_b32 s11, s11, 29
	s_add_i32 s11, s10, s11
	s_and_b32 s13, s11, -8
	s_sub_i32 s10, s10, s13
	s_ashr_i32 s11, s11, 3
	s_cmp_lt_i32 s10, 0
	s_mul_i32 s36, s8, s9
	s_cselect_b32 s13, s4, 0xfffffdd0
	s_abs_i32 s36, s36
	s_mul_i32 s10, s10, s13
	s_sub_i32 s13, 0, s36
	s_sub_i32 s10, s10, s11
	s_addk_i32 s10, 0x117f
	s_ashr_i32 s11, s10, 31
	s_abs_i32 s10, s10
	s_mov_b32 s37, 0xea0ea
	s_mul_hi_u32 s13, s10, s37
	s_mul_i32 s13, s13, s36
	s_sub_i32 s10, s10, s13
	s_sub_i32 s13, s10, s36
	s_cmp_ge_u32 s10, s36
	s_cselect_b32 s10, s13, s10
	s_sub_i32 s13, s10, s36
	s_cmp_ge_u32 s10, s36
	s_cselect_b32 s10, s13, s10
	s_lshl_b32 s9, s9, 2
	s_abs_i32 s13, s9
	s_xor_b32 s10, s10, s11
	s_sub_i32 s10, s10, s11
	s_sub_i32 s11, 0, s13
	s_abs_i32 s37, s10
	s_xor_b32 s36, s10, s9
	s_ashr_i32 s36, s36, 31
	s_mov_b32 s44, 0x2492492
	s_mul_hi_u32 s11, s37, s44
	s_mul_i32 s44, s11, s13
	s_sub_i32 s37, s37, s44
	s_add_i32 s45, s11, 1
	s_sub_i32 s44, s37, s13
	s_cmp_ge_u32 s37, s13
	s_cselect_b32 s11, s45, s11
	s_cselect_b32 s37, s44, s37
	s_add_i32 s44, s11, 1
	s_cmp_ge_u32 s37, s13
	s_cselect_b32 s11, s44, s11
	s_xor_b32 s11, s11, s36
	s_sub_i32 s11, s11, s36
	s_lshl_b32 s13, s11, 2
	s_sub_i32 s8, s8, s13
	s_min_i32 s8, s8, 4
	s_abs_i32 s36, s8
	s_sub_i32 s37, 0, s36
	s_mul_i32 s11, s11, s9
	s_sub_i32 s9, s10, s11
	s_abs_i32 s10, s9
	s_xor_b32 s11, s9, s8
	s_ashr_i32 s11, s11, 31
	s_mov_b32 s44, 0x40000000
	s_mul_hi_u32 s37, s10, s44
	s_mul_i32 s44, s37, s36
	s_sub_i32 s10, s10, s44
	s_add_i32 s45, s37, 1
	s_sub_i32 s44, s10, s36
	s_cmp_ge_u32 s10, s36
	s_cselect_b32 s37, s45, s37
	s_cselect_b32 s10, s44, s10
	s_add_i32 s44, s37, 1
	s_cmp_ge_u32 s10, s36
	s_cselect_b32 s10, s44, s37
	s_xor_b32 s10, s10, s11
	s_sub_i32 s56, s10, s11
	s_mul_i32 s8, s56, s8
	s_sub_i32 s8, s9, s8
	s_add_i32 s58, s13, s8

;     __device__ __forceinline__ bool next(int i, Unit& u) const {
;     ...
;         const long L = (long)i * G + c; if (L >= nwg) return false;
;         int wgid = (int)L; { const int q = nwg / NXCD, r = nwg % NXCD, xcd = wgid % NXCD, off = wgid / NXCD; wgid = (xcd < r ? xcd * (q + 1) : r * (q + 1) + (xcd - r) * q) + off; }
;         if (rev) wgid = nwg - 1 - wgid;
;         const int per = nM * nN, z = wgid / per, rem = wgid - z * per;
;         const int nig = WGM * nN, gid = rem / nig, fm = gid * WGM, gsz = (nM - fm) < WGM ? (nM - fm) : WGM, ri = rem - gid * nig;
;         u.pm = fm + (ri % gsz); u.pn = ri / gsz; u.z1 = z / Z2; u.z2 = z - u.z1 * Z2; return true;
; template <class Epi>
; __device__ __forceinline__ void gemm_phase(PG8_LAS unsigned char* lds, PG8_LAS unsigned char* xl, const Gemm g, const Sched& S, const Epi& E, const int wid) {
;     ...
;     for (int i = 0; i < 2; ++i) { int R, C; stage_rc(tid * 16 + i * 8192, R, C); const int Rb = Epi::PERM ? ((R & ~31) + perm32(R & 31)) : R;
;         const int Ra = Epi::PERM ? ((R & ~63) + 4 * (R & 15) + ((R >> 4) & 3)) : R;
;         voffA[i] = (unsigned)(Ra * g.lda + C) * 2u; voffB[i] = (unsigned)(Rb * g.ldb + C) * 2u; }
;     const size_t kstep = (size_t)(BK * 2);
;     const size_t hstepA = (size_t)HALF * g.lda * 2, hstepB = (size_t)HALF * g.ldb * 2;
;     const unsigned ldsw = (unsigned)wid * 1024u;
;     const int aoff = lds_byte(wr * 64 + fr, fq * 8), boff = lds_byte(wc * 32 + fr, fq * 8);
;     ...
;     Unit cur, nxt; int ui = 0;
;     if (!S.next(0, cur)) return;
;     Acc acc;
; #pragma unroll
;     for (int a = 0; a < 2; ++a)
; #pragma unroll
;         for (int b = 0; b < 2; ++b)
; #pragma unroll
;             for (int m = 0; m < 4; ++m)
; #pragma unroll
;                 for (int n = 0; n < 2; ++n) acc[a][b][m][n] = (f32x4){0.f, 0.f, 0.f, 0.f};
;     bf16x8 At[4][2], B0[2][2], B1[2][2];
;     float prc[8];
; #pragma unroll
;     for (int k = 0; k < 8; ++k) prc[k] = 1.0f;
;     if constexpr (Epi::PRE) { const float* pb = E.pre_base(cur) + wr * 64 + 4 * fr;
; #pragma unroll
;         for (int k = 0; k < 8; ++k) prc[k] = pb[(k >> 2) * HALF + (k & 3)]; }
;     const char* cA = a_tile(g, cur); const char* cB = b_tile(g, cur);
;     PG8_STAGE(PG8_SB(0, 0), cB, voffB); PG8_STAGE(PG8_SB(0, 1), cB + hstepB, voffB); PG8_STAGE(PG8_SA(0, 0), cA, voffA); PG8_STAGE(PG8_SA(0, 1), cA + hstepA, voffA);
;     if (wr == 1) PG8_BAR;
.LBB0_395:
	v_readlane_b32 s0, v254, 27
	v_readlane_b32 s1, v254, 28
	s_mov_b32 s10, 8
	s_mov_b32 s9, 1
	v_cndmask_b32_e64 v0, 0, 1, s[0:1]
	v_cmp_ne_u32_e64 s[4:5], 1, v0
	s_mov_b32 s8, 4
	s_andn2_b64 vcc, exec, s[0:1]
	v_writelane_b32 v252, s4, 54
	v_mbcnt_lo_u32_b32 v8, -1, 0
	v_mbcnt_hi_u32_b32 v8, -1, v8
	s_nop 1
	v_writelane_b32 v252, s5, 55
	s_cbranch_vccnz .LBB0_415
	v_lshlrev_b32_e32 v10, 4, v8
	v_add_u32_e32 v0, s29, v10
	v_add_u32_e32 v1, 0x2000, v0
	v_ashrrev_i32_e32 v2, 31, v1
	v_lshrrev_b32_e32 v2, 22, v2
	v_add_u32_e32 v2, v1, v2
	v_ashrrev_i32_e32 v9, 10, v2
	v_mul_i32_i24_e32 v2, 0x400, v9
	v_sub_u32_e32 v1, v1, v2
	v_lshrrev_b32_e32 v2, 4, v1
	v_bitop3_b32 v1, v2, v1, 32 bitop3:0x6c
	v_ashrrev_i32_e32 v2, 31, v1
	v_lshrrev_b32_e32 v2, 26, v2
	v_add_u32_e32 v2, v1, v2
	v_ashrrev_i32_e32 v3, 6, v2
	v_lshlrev_b32_e32 v4, 3, v9
	v_and_b32_e32 v2, 0xffc0, v2
	v_and_b32_e32 v4, -16, v4
	v_sub_u32_e32 v1, v1, v2
	v_add_u32_e32 v4, v3, v4
	v_lshrrev_b16_e32 v2, 7, v1
	v_and_b32_e32 v3, 3, v3
	s_mov_b32 s4, 0xfffe0
	v_lshrrev_b32_e32 v5, 2, v4
	v_lshlrev_b32_e32 v6, 1, v4
	v_and_b32_e32 v2, 1, v2
	v_and_or_b32 v3, v4, s4, v3
	v_and_b32_e32 v5, 4, v5
	v_and_b32_e32 v6, 24, v6
	v_add_u16_e32 v1, v1, v2
	v_or3_b32 v3, v3, v5, v6
	v_lshlrev_b32_e32 v5, 5, v9
	v_ashrrev_i16_sdwa v1, v244, sext(v1) dst_sel:DWORD dst_unused:UNUSED_PAD src0_sel:DWORD src1_sel:BYTE_0
	v_lshlrev_b32_e32 v2, 2, v4
	v_and_b32_e32 v5, 32, v5
	v_bfe_i32 v11, v1, 0, 16
	v_and_b32_e32 v12, 0x7ffc0, v4
	v_and_b32_e32 v13, 60, v2
	v_bfe_u32 v14, v4, 4, 2
	v_add_lshl_u32 v1, v5, v11, 1
	v_or3_b32 v2, v12, v13, v14
	v_lshl_add_u32 v128, v3, 12, v1
	v_lshl_add_u32 v130, v2, 13, v1
	v_ashrrev_i32_e32 v1, 31, v0
	v_lshrrev_b32_e32 v1, 22, v1
	v_add_u32_e32 v1, v0, v1
	v_ashrrev_i32_e32 v15, 10, v1
	v_mul_i32_i24_e32 v1, 0x400, v15
	v_sub_u32_e32 v0, v0, v1
	v_lshrrev_b32_e32 v1, 4, v0
	v_bitop3_b32 v0, v1, v0, 32 bitop3:0x6c
	s_waitcnt lgkmcnt(0)
	s_add_u32 s0, s50, 0x4800000
	v_ashrrev_i32_e32 v1, 31, v0
	s_addc_u32 s1, s51, 0
	v_lshrrev_b32_e32 v1, 26, v1
	s_add_u32 s62, s50, 0x16000000
	v_add_u32_e32 v1, v0, v1
	s_mul_i32 s11, s9, s10
	s_addc_u32 s66, s51, 0
	v_ashrrev_i32_e32 v2, 6, v1
	v_and_b32_e32 v1, 0xc0, v1
	s_abs_i32 s12, s11
	v_sub_u32_e32 v0, v0, v1
	v_lshlrev_b32_e32 v3, 3, v15
	v_and_b32_e32 v3, -16, v3
	s_sub_i32 s20, 0, s12
	v_add_u32_e32 v3, v2, v3
	v_and_b32_e32 v2, 3, v2
	v_and_or_b32 v2, v3, s4, v2
	s_ashr_i32 s13, s11, 31
	v_readlane_b32 s4, v254, 58
	s_xor_b32 s13, s4, s13
	s_mov_b32 s21, 0x20000000
	v_readlane_b32 s4, v254, 60
	s_mul_hi_u32 s20, s4, s21
	s_mul_i32 s21, s20, s12
	s_sub_i32 s21, s4, s21
	s_add_i32 s30, s20, 1
	s_sub_i32 s31, s21, s12
	s_cmp_ge_u32 s21, s12
	s_cselect_b32 s20, s30, s20
	s_cselect_b32 s21, s31, s21
	s_add_i32 s30, s20, 1
	s_cmp_ge_u32 s21, s12
	s_cselect_b32 s12, s30, s20
	s_lshl_b32 s10, s10, 2
	s_abs_i32 s20, s10
	s_xor_b32 s12, s12, s13
	s_sub_i32 s13, s12, s13
	s_sub_i32 s30, 0, s20
	s_mul_i32 s11, s13, s11
	v_readlane_b32 s4, v254, 59
	s_sub_i32 s11, s4, s11
	s_abs_i32 s21, s11
	s_xor_b32 s12, s11, s10
	s_ashr_i32 s12, s12, 31
	s_mov_b32 s31, 0x8000000
	s_mul_hi_u32 s30, s21, s31
	s_mul_i32 s31, s30, s20
	s_sub_i32 s21, s21, s31
	s_add_i32 s31, s30, 1
	s_sub_i32 s36, s21, s20
	s_cmp_ge_u32 s21, s20
	s_cselect_b32 s30, s31, s30
	s_cselect_b32 s21, s36, s21
	s_add_i32 s31, s30, 1
	s_cmp_ge_u32 s21, s20
	s_cselect_b32 s20, s31, s30
	s_xor_b32 s20, s20, s12
	s_sub_i32 s12, s20, s12
	v_lshrrev_b32_e32 v4, 2, v3
	v_lshlrev_b32_e32 v5, 1, v3
	s_lshl_b32 s20, s12, 2
	v_and_b32_e32 v4, 4, v4
	v_and_b32_e32 v5, 24, v5
	s_sub_i32 s9, s9, s20
	v_or3_b32 v2, v2, v4, v5
	v_lshlrev_b32_e32 v4, 5, v15
	v_ashrrev_i16_sdwa v0, v244, sext(v0) dst_sel:DWORD dst_unused:UNUSED_PAD src0_sel:DWORD src1_sel:BYTE_0
	s_min_i32 s9, s9, 4
	v_and_b32_e32 v4, 32, v4
	v_bfe_i32 v16, v0, 0, 16
	s_abs_i32 s21, s9
	v_add_lshl_u32 v0, v4, v16, 1
	v_cvt_f32_u32_e32 v1, s21
	v_lshl_add_u32 v132, v2, 12, v0
	v_lshlrev_b32_e32 v2, 2, v3
	v_and_b32_e32 v17, 0x7ffc0, v3
	v_and_b32_e32 v18, 60, v2
	v_bfe_u32 v19, v3, 4, 2
	v_or3_b32 v2, v17, v18, v19
	v_lshl_add_u32 v134, v2, 13, v0
	v_rcp_iflag_f32_e32 v0, v1
	s_sub_i32 s30, 0, s21
	s_mul_i32 s12, s12, s10
	s_sub_i32 s10, s11, s12
	v_mul_f32_e32 v0, 0x4f7ffffe, v0
	v_cvt_u32_f32_e32 v0, v0
	s_abs_i32 s12, s10
	s_xor_b32 s11, s10, s9
	s_ashr_i32 s11, s11, 31
	v_readfirstlane_b32 s31, v0
	s_mul_i32 s30, s30, s31
	s_mul_hi_u32 s30, s31, s30
	s_add_i32 s31, s31, s30
	s_mul_hi_u32 s30, s12, s31
	s_mul_i32 s31, s30, s21
	s_sub_i32 s12, s12, s31
	s_add_i32 s31, s30, 1
	s_sub_i32 s36, s12, s21
	s_cmp_ge_u32 s12, s21
	s_cselect_b32 s30, s31, s30
	s_cselect_b32 s12, s36, s12
	s_add_i32 s31, s30, 1
	s_cmp_ge_u32 s12, s21
	s_cselect_b32 s12, s31, s30
	s_abs_i32 s21, s8
	s_xor_b32 s12, s12, s11
	s_sub_i32 s12, s12, s11
	s_mul_i32 s9, s12, s9
	s_sub_i32 s9, s10, s9
	s_add_i32 s36, s20, s9
	s_sub_i32 s11, 0, s21
	s_abs_i32 s10, s13
	s_xor_b32 s9, s13, s8
	s_ashr_i32 s9, s9, 31
	s_mov_b32 s20, 0x40000000
	s_mul_hi_u32 s11, s10, s20
	s_mul_i32 s20, s11, s21
	s_sub_i32 s10, s10, s20
	s_add_i32 s20, s11, 1
	s_sub_i32 s30, s10, s21
	s_cmp_ge_u32 s10, s21
	s_cselect_b32 s11, s20, s11
	s_cselect_b32 s10, s30, s10
	s_add_i32 s20, s11, 1
	s_cmp_ge_u32 s10, s21
	s_cselect_b32 s10, s20, s11
	s_xor_b32 s10, s10, s9
	s_sub_i32 s56, s10, s9
	s_mul_i32 s8, s56, s8
	s_sub_i32 s52, s13, s8
	s_ashr_i32 s57, s56, 31
	s_ashr_i32 s53, s52, 31
	s_lshl_b64 s[8:9], s[56:57], 21
	s_add_u32 s10, s62, s8
	s_addc_u32 s11, s66, s9
	s_lshl_b64 s[8:9], s[52:53], 10
	s_add_u32 s10, s10, s8
	s_addc_u32 s11, s11, s9
	s_ashr_i32 s13, s12, 31
	s_add_u32 s20, s0, s8
	s_addc_u32 s21, s1, s9
	s_lshl_b64 s[8:9], s[12:13], 20
	s_add_u32 s76, s20, s8
	s_addc_u32 s77, s21, s9
	s_add_i32 s13, s29, 0
	s_add_i32 m0, s13, 0x10000
	s_ashr_i32 s37, s36, 31
	global_load_lds_dwordx4 v132, s[76:77]
	s_add_i32 m0, s13, 0x12000
	s_add_u32 s8, s76, 0x80000
	global_load_lds_dwordx4 v128, s[76:77]
	s_addc_u32 s9, s77, 0
	s_add_i32 m0, s13, 0x14000
	v_mov_b32_e32 v133, v193
	global_load_lds_dwordx4 v132, s[8:9]
	s_add_i32 m0, s13, 0x16000
	v_mov_b32_e32 v129, v193
	global_load_lds_dwordx4 v128, s[8:9]
	s_lshl_b64 s[8:9], s[36:37], 21
	s_add_u32 s60, s10, s8
	s_addc_u32 s61, s11, s9
	s_add_i32 s67, s13, 0x2000
	s_mov_b32 m0, s13
	s_add_u32 s8, s60, 0x100000
	global_load_lds_dwordx4 v134, s[60:61]
	s_mov_b32 m0, s67
	s_addc_u32 s9, s61, 0
	s_add_i32 s68, s13, 0x4000
	global_load_lds_dwordx4 v130, s[60:61]
	s_mov_b32 m0, s68
	s_add_i32 s69, s13, 0x6000
	global_load_lds_dwordx4 v134, s[8:9]
	s_mov_b32 m0, s69
	v_mov_b32_e32 v135, v193
	global_load_lds_dwordx4 v130, s[8:9]
	v_mov_b32_e32 v131, v193
	v_lshl_add_u64 v[6:7], s[76:77], 0, v[132:133]
	v_lshl_add_u64 v[4:5], s[76:77], 0, v[128:129]
	v_lshl_add_u64 v[2:3], s[60:61], 0, v[134:135]
	s_and_b64 vcc, exec, s[38:39]
	v_lshl_add_u64 v[0:1], s[60:61], 0, v[130:131]
	s_cbranch_vccnz .LBB0_398
	s_barrier

;     __device__ __forceinline__ bool next(int i, Unit& u) const {
;         int nM = this->nM, nN = this->nN, Z2 = this->Z2; asm volatile("" : "+s"(nM), "+s"(nN), "+s"(Z2));
;         const long L = (long)i * G + c; if (L >= nwg) return false;
;         int wgid = (int)L; { const int q = nwg / NXCD, r = nwg % NXCD, xcd = wgid % NXCD, off = wgid / NXCD; wgid = (xcd < r ? xcd * (q + 1) : r * (q + 1) + (xcd - r) * q) + off; }
;         if (rev) wgid = nwg - 1 - wgid;
;         const int per = nM * nN, z = wgid / per, rem = wgid - z * per;
;         const int nig = WGM * nN, gid = rem / nig, fm = gid * WGM, gsz = (nM - fm) < WGM ? (nM - fm) : WGM, ri = rem - gid * nig;
;         u.pm = fm + (ri % gsz); u.pn = ri / gsz; u.z1 = z / Z2; u.z2 = z - u.z1 * Z2; return true;
; template <class Epi>
; __device__ __forceinline__ void gemm_phase(PG8_LAS unsigned char* lds, PG8_LAS unsigned char* xl, const Gemm g, const Sched& S, const Epi& E, const int wid) {
;     ...
;         const bool has_next = S.next(ui + 1, nxt);
.LBB0_401:
	s_add_i32 s91, s91, 1
	s_mul_i32 s10, s91, s90
	s_mul_hi_u32 s11, s91, s87
	s_add_i32 s11, s11, s10
	s_mul_i32 s10, s91, s87
	s_add_u32 s10, s10, s2
	s_addc_u32 s11, s11, s33
	v_cmp_gt_i64_e32 vcc, s[10:11], v[198:199]
	s_mov_b32 s21, 8
	s_mov_b32 s9, 1
	s_mov_b32 s8, 4
	v_cmp_lt_i64_e64 s[46:47], s[10:11], v[196:197]
	s_cbranch_vccnz .LBB0_403
	s_ashr_i32 s11, s10, 31
	s_lshr_b32 s11, s11, 29
	s_add_i32 s11, s10, s11
	s_ashr_i32 s20, s11, 3
	s_and_b32 s11, s11, -8
	s_sub_i32 s10, s10, s11
	s_cmp_lt_i32 s10, 0
	s_movk_i32 s4, 0x51
	s_mul_i32 s30, s9, s21
	s_cselect_b32 s11, s4, 0x50
	s_abs_i32 s31, s30
	s_mul_i32 s10, s10, s11
	s_sub_i32 s11, 0, s31
	s_add_i32 s10, s10, s20
	s_abs_i32 s37, s10
	s_xor_b32 s20, s10, s30
	s_ashr_i32 s20, s20, 31
	s_mov_b32 s40, 0x20000000
	s_mul_hi_u32 s11, s37, s40
	s_mul_i32 s40, s11, s31
	s_sub_i32 s37, s37, s40
	s_add_i32 s40, s11, 1
	s_sub_i32 s41, s37, s31
	s_cmp_ge_u32 s37, s31
	s_cselect_b32 s11, s40, s11
	s_cselect_b32 s37, s41, s37
	s_add_i32 s40, s11, 1
	s_cmp_ge_u32 s37, s31
	s_cselect_b32 s11, s40, s11
	s_lshl_b32 s21, s21, 2
	s_abs_i32 s31, s21
	s_xor_b32 s11, s11, s20
	s_sub_i32 s11, s11, s20
	s_sub_i32 s37, 0, s31
	s_mul_i32 s20, s11, s30
	s_sub_i32 s10, s10, s20
	s_abs_i32 s30, s10
	s_xor_b32 s20, s10, s21
	s_ashr_i32 s20, s20, 31
	s_mov_b32 s40, 0x8000000
	s_mul_hi_u32 s37, s30, s40
	s_mul_i32 s40, s37, s31
	s_sub_i32 s30, s30, s40
	s_add_i32 s40, s37, 1
	s_sub_i32 s41, s30, s31
	s_cmp_ge_u32 s30, s31
	s_cselect_b32 s37, s40, s37
	s_cselect_b32 s30, s41, s30
	s_add_i32 s40, s37, 1
	s_cmp_ge_u32 s30, s31
	s_cselect_b32 s30, s40, s37
	s_xor_b32 s30, s30, s20
	s_sub_i32 s20, s30, s20
	s_lshl_b32 s30, s20, 2
	s_sub_i32 s9, s9, s30
	s_min_i32 s9, s9, 4
	s_abs_i32 s31, s9
	v_cvt_f32_u32_e32 v0, s31
	s_sub_i32 s37, 0, s31
	s_mul_i32 s20, s20, s21
	s_sub_i32 s10, s10, s20
	v_rcp_iflag_f32_e32 v0, v0
	s_abs_i32 s21, s10
	s_xor_b32 s20, s10, s9
	s_ashr_i32 s20, s20, 31
	v_mul_f32_e32 v0, 0x4f7ffffe, v0
	v_cvt_u32_f32_e32 v0, v0
	s_nop 0
	v_readfirstlane_b32 s40, v0
	s_mul_i32 s37, s37, s40
	s_mul_hi_u32 s37, s40, s37
	s_add_i32 s40, s40, s37
	s_mul_hi_u32 s37, s21, s40
	s_mul_i32 s40, s37, s31
	s_sub_i32 s21, s21, s40
	s_add_i32 s40, s37, 1
	s_sub_i32 s41, s21, s31
	s_cmp_ge_u32 s21, s31
	s_cselect_b32 s37, s40, s37
	s_cselect_b32 s21, s41, s21
	s_add_i32 s40, s37, 1
	s_cmp_ge_u32 s21, s31
	s_cselect_b32 s21, s40, s37
	s_abs_i32 s31, s8
	s_xor_b32 s21, s21, s20
	s_sub_i32 s20, s21, s20
	s_sub_i32 s21, 0, s31
	s_mul_i32 s9, s20, s9
	s_sub_i32 s9, s10, s9
	s_abs_i32 s10, s11
	s_add_i32 s30, s30, s9
	s_xor_b32 s9, s11, s8
	s_ashr_i32 s9, s9, 31
	s_mov_b32 s37, 0x40000000
	s_mul_hi_u32 s21, s10, s37
	s_mul_i32 s37, s21, s31
	s_sub_i32 s10, s10, s37
	s_add_i32 s37, s21, 1
	s_sub_i32 s40, s10, s31
	s_cmp_ge_u32 s10, s31
	s_cselect_b32 s21, s37, s21
	s_cselect_b32 s10, s40, s10
	s_add_i32 s37, s21, 1
	s_cmp_ge_u32 s10, s31
	s_cselect_b32 s10, s37, s21
	s_xor_b32 s10, s10, s9
	s_sub_i32 s44, s10, s9
	s_mul_i32 s8, s44, s8
	s_sub_i32 s48, s11, s8

;     __device__ __forceinline__ bool next(int i, Unit& u) const {
;         int nM = this->nM, nN = this->nN, Z2 = this->Z2; asm volatile("" : "+s"(nM), "+s"(nN), "+s"(Z2));
;         const long L = (long)i * G + c; if (L >= nwg) return false;
; template <class Epi>
; __device__ __forceinline__ void gemm_phase(PG8_LAS unsigned char* lds, PG8_LAS unsigned char* xl, const Gemm g, const Sched& S, const Epi& E, const int wid) {
;     ...
;     if (!S.next(0, cur)) return;
.LBB0_415:
	v_readlane_b32 s0, v254, 13
	s_add_i32 s0, s87, s0
	v_readlane_b32 s90, v252, 30
	v_readlane_b32 s72, v252, 34
	v_readlane_b32 s76, v252, 36
	v_readlane_b32 s88, v252, 38
	s_mov_b32 s9, 8
	s_mov_b32 s10, 1
	s_mov_b32 s8, 4
	s_cmpk_gt_i32 s0, 0x27f
	v_readlane_b32 s91, v252, 31
	v_readlane_b32 s73, v252, 35
	v_readlane_b32 s77, v252, 37
	v_readlane_b32 s89, v252, 39
	v_mbcnt_lo_u32_b32 v8, -1, 0
	v_mbcnt_hi_u32_b32 v8, -1, v8
	s_cbranch_scc1 .LBB0_435
;     __device__ __forceinline__ bool next(int i, Unit& u) const {
;     ...
;         const long L = (long)i * G + c; if (L >= nwg) return false;
;         int wgid = (int)L; { const int q = nwg / NXCD, r = nwg % NXCD, xcd = wgid % NXCD, off = wgid / NXCD; wgid = (xcd < r ? xcd * (q + 1) : r * (q + 1) + (xcd - r) * q) + off; }
;         if (rev) wgid = nwg - 1 - wgid;
;         const int per = nM * nN, z = wgid / per, rem = wgid - z * per;
;         const int nig = WGM * nN, gid = rem / nig, fm = gid * WGM, gsz = (nM - fm) < WGM ? (nM - fm) : WGM, ri = rem - gid * nig;
;         u.pm = fm + (ri % gsz); u.pn = ri / gsz; u.z1 = z / Z2; u.z2 = z - u.z1 * Z2; return true;
; template <class Epi>
; __device__ __forceinline__ void gemm_phase(PG8_LAS unsigned char* lds, PG8_LAS unsigned char* xl, const Gemm g, const Sched& S, const Epi& E, const int wid) {
;     ...
;     for (int i = 0; i < 2; ++i) { int R, C; stage_rc(tid * 16 + i * 8192, R, C); const int Rb = Epi::PERM ? ((R & ~31) + perm32(R & 31)) : R;
;         const int Ra = Epi::PERM ? ((R & ~63) + 4 * (R & 15) + ((R >> 4) & 3)) : R;
;         voffA[i] = (unsigned)(Ra * g.lda + C) * 2u; voffB[i] = (unsigned)(Rb * g.ldb + C) * 2u; }
;     const size_t kstep = (size_t)(BK * 2);
;     const size_t hstepA = (size_t)HALF * g.lda * 2, hstepB = (size_t)HALF * g.ldb * 2;
;     const unsigned ldsw = (unsigned)wid * 1024u;
;     const int aoff = lds_byte(wr * 64 + fr, fq * 8), boff = lds_byte(wc * 32 + fr, fq * 8);
;     ...
;     Unit cur, nxt; int ui = 0;
;     if (!S.next(0, cur)) return;
;     Acc acc;
; #pragma unroll
;     for (int a = 0; a < 2; ++a)
; #pragma unroll
;         for (int b = 0; b < 2; ++b)
; #pragma unroll
;             for (int m = 0; m < 4; ++m)
; #pragma unroll
;                 for (int n = 0; n < 2; ++n) acc[a][b][m][n] = (f32x4){0.f, 0.f, 0.f, 0.f};
;     bf16x8 At[4][2], B0[2][2], B1[2][2];
;     float prc[8];
; #pragma unroll
;     for (int k = 0; k < 8; ++k) prc[k] = 1.0f;
;     if constexpr (Epi::PRE) { const float* pb = E.pre_base(cur) + wr * 64 + 4 * fr;
; #pragma unroll
;         for (int k = 0; k < 8; ++k) prc[k] = pb[(k >> 2) * HALF + (k & 3)]; }
;     const char* cA = a_tile(g, cur); const char* cB = b_tile(g, cur);
;     PG8_STAGE(PG8_SB(0, 0), cB, voffB); PG8_STAGE(PG8_SB(0, 1), cB + hstepB, voffB); PG8_STAGE(PG8_SA(0, 0), cA, voffA); PG8_STAGE(PG8_SA(0, 1), cA + hstepA, voffA);
;     if (wr == 1) PG8_BAR;
	v_lshlrev_b32_e32 v10, 4, v8
	v_add_u32_e32 v0, s29, v10
	v_add_u32_e32 v1, 0x2000, v0
	v_ashrrev_i32_e32 v2, 31, v1
	v_lshrrev_b32_e32 v2, 22, v2
	v_add_u32_e32 v2, v1, v2
	v_ashrrev_i32_e32 v9, 10, v2
	v_mul_i32_i24_e32 v2, 0x400, v9
	v_sub_u32_e32 v1, v1, v2
	v_lshrrev_b32_e32 v2, 4, v1
	v_bitop3_b32 v1, v2, v1, 32 bitop3:0x6c
	v_ashrrev_i32_e32 v2, 31, v1
	v_lshrrev_b32_e32 v2, 26, v2
	v_add_u32_e32 v2, v1, v2
	v_ashrrev_i32_e32 v3, 6, v2
	v_lshlrev_b32_e32 v4, 3, v9
	v_and_b32_e32 v2, 0xffc0, v2
	v_and_b32_e32 v4, -16, v4
	v_sub_u32_e32 v1, v1, v2
	v_add_u32_e32 v4, v3, v4
	v_lshrrev_b16_e32 v2, 7, v1
	v_and_b32_e32 v3, 3, v3
	s_mov_b32 s4, 0x7ffe0
	v_lshrrev_b32_e32 v5, 2, v4
	v_lshlrev_b32_e32 v6, 1, v4
	v_and_b32_e32 v2, 1, v2
	v_and_or_b32 v3, v4, s4, v3
	v_and_b32_e32 v5, 4, v5
	v_and_b32_e32 v6, 24, v6
	v_add_u16_e32 v1, v1, v2
	v_or3_b32 v3, v3, v5, v6
	v_lshlrev_b32_e32 v5, 5, v9
	v_ashrrev_i16_sdwa v1, v244, sext(v1) dst_sel:DWORD dst_unused:UNUSED_PAD src0_sel:DWORD src1_sel:BYTE_0
	v_lshlrev_b32_e32 v2, 2, v4
	v_and_b32_e32 v5, 32, v5
	v_bfe_i32 v11, v1, 0, 16
	v_and_b32_e32 v12, 0xfffc0, v4
	v_and_b32_e32 v13, 60, v2
	v_bfe_u32 v14, v4, 4, 2
	v_add_lshl_u32 v1, v5, v11, 1
	v_or3_b32 v2, v12, v13, v14
	v_lshl_add_u32 v128, v3, 13, v1
	v_lshl_add_u32 v130, v2, 12, v1
	v_ashrrev_i32_e32 v1, 31, v0
	v_lshrrev_b32_e32 v1, 22, v1
	v_add_u32_e32 v1, v0, v1
	v_ashrrev_i32_e32 v15, 10, v1
	v_mul_i32_i24_e32 v1, 0x400, v15
	s_waitcnt lgkmcnt(0)
	s_add_u32 s1, s50, 0x6000000
	v_sub_u32_e32 v0, v0, v1
	s_addc_u32 s62, s51, 0
	v_lshrrev_b32_e32 v1, 4, v0
	s_add_u32 s66, s50, 0x16001000
	v_bitop3_b32 v0, v1, v0, 32 bitop3:0x6c
	s_addc_u32 s67, s51, 0
	v_ashrrev_i32_e32 v1, 31, v0
	s_ashr_i32 s68, s0, 31
	v_lshrrev_b32_e32 v1, 26, v1
	s_lshr_b32 s11, s68, 29
	v_add_u32_e32 v1, v0, v1
	v_lshlrev_b32_e32 v3, 3, v15
	s_add_i32 s11, s0, s11
	v_ashrrev_i32_e32 v2, 6, v1
	v_and_b32_e32 v3, -16, v3
	s_ashr_i32 s12, s11, 3
	s_and_b32 s11, s11, -8
	v_add_u32_e32 v3, v2, v3
	v_and_b32_e32 v2, 3, v2
	s_sub_i32 s11, s0, s11
	v_and_or_b32 v2, v3, s4, v2
	s_cmp_lt_i32 s11, 0
	s_movk_i32 s4, 0x51
	s_mul_i32 s20, s9, s10
	v_and_b32_e32 v1, 0xc0, v1
	s_cselect_b32 s13, s4, 0x50
	s_abs_i32 s21, s20
	v_sub_u32_e32 v0, v0, v1
	s_sub_i32 s30, 0, s21
	s_mul_i32 s11, s11, s13
	s_add_i32 s11, s11, s12
	s_abs_i32 s13, s11
	s_xor_b32 s12, s11, s20
	s_ashr_i32 s12, s12, 31
	v_lshrrev_b32_e32 v4, 2, v3
	v_lshlrev_b32_e32 v5, 1, v3
	v_and_b32_e32 v4, 4, v4
	s_mov_b32 s31, 0x20000000
	s_mul_hi_u32 s30, s13, s31
	s_mul_i32 s31, s30, s21
	s_sub_i32 s13, s13, s31
	s_add_i32 s31, s30, 1
	s_sub_i32 s36, s13, s21
	s_cmp_ge_u32 s13, s21
	s_cselect_b32 s30, s31, s30
	s_cselect_b32 s13, s36, s13
	s_add_i32 s31, s30, 1
	s_cmp_ge_u32 s13, s21
	s_cselect_b32 s13, s31, s30
	s_lshl_b32 s10, s10, 2
	s_abs_i32 s21, s10
	s_xor_b32 s13, s13, s12
	s_sub_i32 s13, s13, s12
	s_sub_i32 s30, 0, s21
	s_mul_i32 s12, s13, s20
	s_sub_i32 s11, s11, s12
	s_abs_i32 s20, s11
	s_xor_b32 s12, s11, s10
	s_ashr_i32 s12, s12, 31
	v_and_b32_e32 v5, 24, v5
	s_mov_b32 s31, 0x40000000
	s_mul_hi_u32 s30, s20, s31
	s_mul_i32 s31, s30, s21
	s_sub_i32 s20, s20, s31
	s_add_i32 s31, s30, 1
	s_sub_i32 s36, s20, s21
	s_cmp_ge_u32 s20, s21
	s_cselect_b32 s30, s31, s30
	s_cselect_b32 s20, s36, s20
	s_add_i32 s31, s30, 1
	s_cmp_ge_u32 s20, s21
	s_cselect_b32 s20, s31, s30
	s_xor_b32 s20, s20, s12
	s_sub_i32 s12, s20, s12
	s_lshl_b32 s20, s12, 2
	s_sub_i32 s9, s9, s20
	v_or3_b32 v2, v2, v4, v5
	v_lshlrev_b32_e32 v4, 5, v15
	v_ashrrev_i16_sdwa v0, v244, sext(v0) dst_sel:DWORD dst_unused:UNUSED_PAD src0_sel:DWORD src1_sel:BYTE_0
	s_min_i32 s9, s9, 4
	v_and_b32_e32 v4, 32, v4
	v_bfe_i32 v16, v0, 0, 16
	s_abs_i32 s21, s9
	v_add_lshl_u32 v0, v4, v16, 1
	v_cvt_f32_u32_e32 v1, s21
	v_lshl_add_u32 v132, v2, 13, v0
	v_lshlrev_b32_e32 v2, 2, v3
	v_and_b32_e32 v17, 0xfffc0, v3
	v_and_b32_e32 v18, 60, v2
	v_bfe_u32 v19, v3, 4, 2
	v_or3_b32 v2, v17, v18, v19
	v_lshl_add_u32 v134, v2, 12, v0
	v_rcp_iflag_f32_e32 v0, v1
	s_sub_i32 s30, 0, s21
	s_mul_i32 s12, s12, s10
	s_sub_i32 s10, s11, s12
	v_mul_f32_e32 v0, 0x4f7ffffe, v0
	v_cvt_u32_f32_e32 v0, v0
	s_abs_i32 s12, s10
	s_xor_b32 s11, s10, s9
	s_ashr_i32 s11, s11, 31
	v_readfirstlane_b32 s31, v0
	s_mul_i32 s30, s30, s31
	s_mul_hi_u32 s30, s31, s30
	s_add_i32 s31, s31, s30
	s_mul_hi_u32 s30, s12, s31
	s_mul_i32 s31, s30, s21
	s_sub_i32 s12, s12, s31
	s_add_i32 s31, s30, 1
	s_sub_i32 s36, s12, s21
	s_cmp_ge_u32 s12, s21
	s_cselect_b32 s30, s31, s30
	s_cselect_b32 s12, s36, s12
	s_add_i32 s31, s30, 1
	s_cmp_ge_u32 s12, s21
	s_cselect_b32 s12, s31, s30
	s_abs_i32 s21, s8
	s_xor_b32 s12, s12, s11
	s_sub_i32 s12, s12, s11
	s_sub_i32 s11, 0, s21
	s_mul_i32 s9, s12, s9
	s_sub_i32 s9, s10, s9
	s_abs_i32 s10, s13
	s_add_i32 s20, s20, s9
	s_xor_b32 s9, s13, s8
	s_ashr_i32 s9, s9, 31
	s_mov_b32 s30, 0x40000000
	s_mul_hi_u32 s11, s10, s30
	s_mul_i32 s30, s11, s21
	s_sub_i32 s10, s10, s30
	s_add_i32 s30, s11, 1
	s_sub_i32 s31, s10, s21
	s_cmp_ge_u32 s10, s21
	s_cselect_b32 s11, s30, s11
	s_cselect_b32 s10, s31, s10
	s_add_i32 s30, s11, 1
	s_cmp_ge_u32 s10, s21
	s_cselect_b32 s10, s30, s11
	s_xor_b32 s10, s10, s9
	s_sub_i32 s48, s10, s9
	s_mul_i32 s8, s48, s8
	s_sub_i32 s44, s13, s8
	s_ashr_i32 s45, s44, 31
	s_ashr_i32 s49, s48, 31
	s_lshl_b64 s[8:9], s[44:45], 10
	s_add_u32 s30, s1, s8
	s_addc_u32 s31, s62, s9
	s_ashr_i32 s13, s12, 31
	s_lshl_b64 s[10:11], s[48:49], 21
	s_add_u32 s10, s66, s10
	s_addc_u32 s11, s67, s11
	s_add_u32 s10, s10, s8
	s_addc_u32 s11, s11, s9
	s_lshl_b64 s[8:9], s[12:13], 21
	s_add_u32 s60, s10, s8
	s_addc_u32 s61, s11, s9
	s_add_i32 s13, s29, 0
	s_add_i32 m0, s13, 0x10000
	s_ashr_i32 s21, s20, 31
	global_load_lds_dwordx4 v132, s[60:61]
	s_add_i32 m0, s13, 0x12000
	s_add_u32 s8, s60, 0x100000
	global_load_lds_dwordx4 v128, s[60:61]
	s_addc_u32 s9, s61, 0
	s_add_i32 m0, s13, 0x14000
	v_mov_b32_e32 v133, v193
	global_load_lds_dwordx4 v132, s[8:9]
	s_add_i32 m0, s13, 0x16000
	v_mov_b32_e32 v129, v193
	global_load_lds_dwordx4 v128, s[8:9]
	s_lshl_b64 s[8:9], s[20:21], 20
	s_add_u32 s58, s30, s8
	s_addc_u32 s59, s31, s9
	s_add_i32 s69, s13, 0x2000
	s_mov_b32 m0, s13
	s_add_u32 s8, s58, 0x80000
	global_load_lds_dwordx4 v134, s[58:59]
	s_mov_b32 m0, s69
	s_addc_u32 s9, s59, 0
	s_add_i32 s70, s13, 0x4000
	global_load_lds_dwordx4 v130, s[58:59]
	s_mov_b32 m0, s70
	s_add_i32 s71, s13, 0x6000
	global_load_lds_dwordx4 v134, s[8:9]
	s_mov_b32 m0, s71
	v_mov_b32_e32 v135, v193
	global_load_lds_dwordx4 v130, s[8:9]
	v_mov_b32_e32 v131, v193
	v_lshl_add_u64 v[6:7], s[60:61], 0, v[132:133]
	v_lshl_add_u64 v[4:5], s[60:61], 0, v[128:129]
	v_lshl_add_u64 v[2:3], s[58:59], 0, v[134:135]
	s_and_b64 vcc, exec, s[38:39]
	v_lshl_add_u64 v[0:1], s[58:59], 0, v[130:131]
	s_cbranch_vccnz .LBB0_418
	s_barrier

;     __device__ __forceinline__ bool next(int i, Unit& u) const {
;         int nM = this->nM, nN = this->nN, Z2 = this->Z2; asm volatile("" : "+s"(nM), "+s"(nN), "+s"(Z2));
;         const long L = (long)i * G + c; if (L >= nwg) return false;
;         int wgid = (int)L; { const int q = nwg / NXCD, r = nwg % NXCD, xcd = wgid % NXCD, off = wgid / NXCD; wgid = (xcd < r ? xcd * (q + 1) : r * (q + 1) + (xcd - r) * q) + off; }
;         if (rev) wgid = nwg - 1 - wgid;
;         const int per = nM * nN, z = wgid / per, rem = wgid - z * per;
;         const int nig = WGM * nN, gid = rem / nig, fm = gid * WGM, gsz = (nM - fm) < WGM ? (nM - fm) : WGM, ri = rem - gid * nig;
;         u.pm = fm + (ri % gsz); u.pn = ri / gsz; u.z1 = z / Z2; u.z2 = z - u.z1 * Z2; return true;
; template <class Epi>
; __device__ __forceinline__ void gemm_phase(PG8_LAS unsigned char* lds, PG8_LAS unsigned char* xl, const Gemm g, const Sched& S, const Epi& E, const int wid) {
;     ...
;         const bool has_next = S.next(ui + 1, nxt);
.LBB0_421:
	s_add_i32 s93, s93, 1
	s_mul_i32 s10, s93, s92
	s_mul_hi_u32 s11, s93, s87
	s_add_i32 s11, s11, s10
	s_mul_i32 s10, s93, s87
	s_add_u32 s10, s10, s0
	s_addc_u32 s11, s11, s68
	v_cmp_gt_i64_e32 vcc, s[10:11], v[198:199]
	s_mov_b32 s9, 8
	s_mov_b32 s21, 1
	s_mov_b32 s8, 4
	v_cmp_lt_i64_e64 s[46:47], s[10:11], v[196:197]
	s_cbranch_vccnz .LBB0_423
	s_ashr_i32 s11, s10, 31
	s_lshr_b32 s11, s11, 29
	s_add_i32 s11, s10, s11
	s_ashr_i32 s30, s11, 3
	s_and_b32 s11, s11, -8
	s_sub_i32 s10, s10, s11
	s_cmp_lt_i32 s10, 0
	s_movk_i32 s4, 0x51
	s_mul_i32 s31, s9, s21
	s_cselect_b32 s11, s4, 0x50
	s_abs_i32 s36, s31
	s_mul_i32 s10, s10, s11
	s_sub_i32 s11, 0, s36
	s_add_i32 s10, s10, s30
	s_abs_i32 s37, s10
	s_xor_b32 s30, s10, s31
	s_ashr_i32 s30, s30, 31
	s_mov_b32 s40, 0x20000000
	s_mul_hi_u32 s11, s37, s40
	s_mul_i32 s40, s11, s36
	s_sub_i32 s37, s37, s40
	s_add_i32 s40, s11, 1
	s_sub_i32 s41, s37, s36
	s_cmp_ge_u32 s37, s36
	s_cselect_b32 s11, s40, s11
	s_cselect_b32 s37, s41, s37
	s_add_i32 s40, s11, 1
	s_cmp_ge_u32 s37, s36
	s_cselect_b32 s11, s40, s11
	s_lshl_b32 s21, s21, 2
	s_abs_i32 s36, s21
	s_xor_b32 s11, s11, s30
	s_sub_i32 s11, s11, s30
	s_sub_i32 s37, 0, s36
	s_mul_i32 s30, s11, s31
	s_sub_i32 s10, s10, s30
	s_abs_i32 s31, s10
	s_xor_b32 s30, s10, s21
	s_ashr_i32 s30, s30, 31
	s_mov_b32 s40, 0x40000000
	s_mul_hi_u32 s37, s31, s40
	s_mul_i32 s40, s37, s36
	s_sub_i32 s31, s31, s40
	s_add_i32 s40, s37, 1
	s_sub_i32 s41, s31, s36
	s_cmp_ge_u32 s31, s36
	s_cselect_b32 s37, s40, s37
	s_cselect_b32 s31, s41, s31
	s_add_i32 s40, s37, 1
	s_cmp_ge_u32 s31, s36
	s_cselect_b32 s31, s40, s37
	s_xor_b32 s31, s31, s30
	s_sub_i32 s30, s31, s30
	s_lshl_b32 s31, s30, 2
	s_sub_i32 s9, s9, s31
	s_min_i32 s9, s9, 4
	s_abs_i32 s36, s9
	s_sub_i32 s37, 0, s36
	s_mul_i32 s30, s30, s21
	s_sub_i32 s10, s10, s30
	s_abs_i32 s30, s10
	s_xor_b32 s21, s10, s9
	s_ashr_i32 s21, s21, 31
	s_mov_b32 s40, 0x40000000
	s_mul_hi_u32 s37, s30, s40
	s_mul_i32 s40, s37, s36
	s_sub_i32 s30, s30, s40
	s_add_i32 s40, s37, 1
	s_sub_i32 s41, s30, s36
	s_cmp_ge_u32 s30, s36
	s_cselect_b32 s37, s40, s37
	s_cselect_b32 s30, s41, s30
	s_add_i32 s40, s37, 1
	s_cmp_ge_u32 s30, s36
	s_cselect_b32 s30, s40, s37
	s_abs_i32 s37, s8
	s_xor_b32 s30, s30, s21
	s_sub_i32 s30, s30, s21
	s_mul_i32 s9, s30, s9
	s_sub_i32 s9, s10, s9
	s_add_i32 s36, s31, s9
	s_sub_i32 s21, 0, s37
	s_abs_i32 s10, s11
	s_xor_b32 s9, s11, s8
	s_ashr_i32 s9, s9, 31
	s_mov_b32 s31, 0x40000000
	s_mul_hi_u32 s21, s10, s31
	s_mul_i32 s31, s21, s37
	s_sub_i32 s10, s10, s31
	s_add_i32 s31, s21, 1
	s_sub_i32 s40, s10, s37
	s_cmp_ge_u32 s10, s37
	s_cselect_b32 s21, s31, s21
	s_cselect_b32 s10, s40, s10
	s_add_i32 s31, s21, 1
	s_cmp_ge_u32 s10, s37
	s_cselect_b32 s10, s31, s21
	s_xor_b32 s10, s10, s9
	s_sub_i32 s50, s10, s9
	s_mul_i32 s8, s50, s8
	s_sub_i32 s52, s11, s8

;     __device__ __forceinline__ bool next(int i, Unit& u) const {
;         int nM = this->nM, nN = this->nN, Z2 = this->Z2; asm volatile("" : "+s"(nM), "+s"(nN), "+s"(Z2));
;         const long L = (long)i * G + c; if (L >= nwg) return false;
; template <class Epi>
; __device__ __forceinline__ void gemm_phase(PG8_LAS unsigned char* lds, PG8_LAS unsigned char* xl, const Gemm g, const Sched& S, const Epi& E, const int wid) {
;     ...
;     if (!S.next(0, cur)) return;
.LBB0_498:
	v_readlane_b32 s4, v254, 34
	v_readlane_b32 s5, v254, 35
	s_mov_b32 s11, 8
	s_mov_b32 s10, 1
	v_cndmask_b32_e64 v0, 0, 1, s[4:5]
	v_cmp_ne_u32_e64 s[8:9], 1, v0
	s_mov_b32 s12, 1
	s_andn2_b64 vcc, exec, s[4:5]
	v_writelane_b32 v252, s8, 46
	v_mbcnt_lo_u32_b32 v8, -1, 0
	v_mbcnt_hi_u32_b32 v8, -1, v8
	s_nop 1
	v_writelane_b32 v252, s9, 47
	s_cbranch_vccnz .LBB0_516
;     __device__ __forceinline__ bool next(int i, Unit& u) const {
;     ...
;         const long L = (long)i * G + c; if (L >= nwg) return false;
;         int wgid = (int)L; { const int q = nwg / NXCD, r = nwg % NXCD, xcd = wgid % NXCD, off = wgid / NXCD; wgid = (xcd < r ? xcd * (q + 1) : r * (q + 1) + (xcd - r) * q) + off; }
;         if (rev) wgid = nwg - 1 - wgid;
;         const int per = nM * nN, z = wgid / per, rem = wgid - z * per;
;         const int nig = WGM * nN, gid = rem / nig, fm = gid * WGM, gsz = (nM - fm) < WGM ? (nM - fm) : WGM, ri = rem - gid * nig;
;         u.pm = fm + (ri % gsz); u.pn = ri / gsz; u.z1 = z / Z2; u.z2 = z - u.z1 * Z2; return true;
; template <class Epi>
; __device__ __forceinline__ void gemm_phase(PG8_LAS unsigned char* lds, PG8_LAS unsigned char* xl, const Gemm g, const Sched& S, const Epi& E, const int wid) {
;     ...
;     for (int i = 0; i < 2; ++i) { int R, C; stage_rc(tid * 16 + i * 8192, R, C); const int Rb = Epi::PERM ? ((R & ~31) + perm32(R & 31)) : R;
;         const int Ra = Epi::PERM ? ((R & ~63) + 4 * (R & 15) + ((R >> 4) & 3)) : R;
;         voffA[i] = (unsigned)(Ra * g.lda + C) * 2u; voffB[i] = (unsigned)(Rb * g.ldb + C) * 2u; }
;     const size_t kstep = (size_t)(BK * 2);
;     const size_t hstepA = (size_t)HALF * g.lda * 2, hstepB = (size_t)HALF * g.ldb * 2;
;     const unsigned ldsw = (unsigned)wid * 1024u;
;     const int aoff = lds_byte(wr * 64 + fr, fq * 8), boff = lds_byte(wc * 32 + fr, fq * 8);
;     ...
;     Unit cur, nxt; int ui = 0;
;     if (!S.next(0, cur)) return;
;     Acc acc;
; #pragma unroll
;     for (int a = 0; a < 2; ++a)
; #pragma unroll
;         for (int b = 0; b < 2; ++b)
; #pragma unroll
;             for (int m = 0; m < 4; ++m)
; #pragma unroll
;                 for (int n = 0; n < 2; ++n) acc[a][b][m][n] = (f32x4){0.f, 0.f, 0.f, 0.f};
;     bf16x8 At[4][2], B0[2][2], B1[2][2];
;     float prc[8];
; #pragma unroll
;     for (int k = 0; k < 8; ++k) prc[k] = 1.0f;
;     if constexpr (Epi::PRE) { const float* pb = E.pre_base(cur) + wr * 64 + 4 * fr;
; #pragma unroll
;         for (int k = 0; k < 8; ++k) prc[k] = pb[(k >> 2) * HALF + (k & 3)]; }
;     const char* cA = a_tile(g, cur); const char* cB = b_tile(g, cur);
;     PG8_STAGE(PG8_SB(0, 0), cB, voffB); PG8_STAGE(PG8_SB(0, 1), cB + hstepB, voffB); PG8_STAGE(PG8_SA(0, 0), cA, voffA); PG8_STAGE(PG8_SA(0, 1), cA + hstepA, voffA);
;     if (wr == 1) PG8_BAR;
	v_lshlrev_b32_e32 v9, 4, v8
	v_add_u32_e32 v0, s29, v9
	v_add_u32_e32 v1, 0x2000, v0
	v_ashrrev_i32_e32 v2, 31, v1
	v_lshrrev_b32_e32 v2, 22, v2
	v_add_u32_e32 v2, v1, v2
	v_ashrrev_i32_e32 v2, 10, v2
	v_mul_i32_i24_e32 v3, 0x400, v2
	v_sub_u32_e32 v1, v1, v3
	v_lshrrev_b32_e32 v3, 4, v1
	v_bitop3_b32 v1, v3, v1, 32 bitop3:0x6c
	v_ashrrev_i32_e32 v3, 31, v1
	v_lshrrev_b32_e32 v3, 26, v3
	v_add_u32_e32 v3, v1, v3
	v_ashrrev_i32_e32 v4, 6, v3
	v_and_b32_e32 v3, 0xffc0, v3
	v_sub_u32_e32 v1, v1, v3
	v_lshlrev_b32_e32 v5, 3, v2
	v_lshrrev_b16_e32 v3, 7, v1
	v_and_b32_e32 v5, -16, v5
	v_and_b32_e32 v3, 1, v3
	v_add_u32_e32 v5, v4, v5
	v_add_u16_e32 v1, v1, v3
	v_and_b32_e32 v4, 3, v4
	s_mov_b32 s4, 0x7fffe0
	v_lshrrev_b32_e32 v6, 2, v5
	v_lshlrev_b32_e32 v7, 1, v5
	v_lshlrev_b32_e32 v2, 5, v2
	v_ashrrev_i16_sdwa v1, v244, sext(v1) dst_sel:DWORD dst_unused:UNUSED_PAD src0_sel:DWORD src1_sel:BYTE_0
	v_and_or_b32 v4, v5, s4, v4
	v_and_b32_e32 v6, 4, v6
	v_and_b32_e32 v7, 24, v7
	v_and_b32_e32 v2, 32, v2
	v_bfe_i32 v1, v1, 0, 16
	v_or3_b32 v4, v4, v6, v7
	v_add_lshl_u32 v1, v2, v1, 1
	v_lshlrev_b32_e32 v3, 2, v5
	v_lshl_add_u32 v210, v4, 9, v1
	v_and_b32_e32 v2, 0x7fffc0, v5
	v_and_b32_e32 v3, 60, v3
	v_bfe_u32 v4, v5, 4, 2
	v_or3_b32 v2, v2, v3, v4
	v_lshl_add_u32 v212, v2, 9, v1
	v_ashrrev_i32_e32 v1, 31, v0
	v_lshrrev_b32_e32 v1, 22, v1
	v_add_u32_e32 v1, v0, v1
	v_ashrrev_i32_e32 v1, 10, v1
	v_mul_i32_i24_e32 v2, 0x400, v1
	v_sub_u32_e32 v0, v0, v2
	v_lshrrev_b32_e32 v2, 4, v0
	v_bitop3_b32 v0, v2, v0, 32 bitop3:0x6c
	v_ashrrev_i32_e32 v2, 31, v0
	v_lshrrev_b32_e32 v2, 26, v2
	v_add_u32_e32 v2, v0, v2
	v_lshlrev_b32_e32 v4, 3, v1
	v_ashrrev_i32_e32 v3, 6, v2
	v_and_b32_e32 v4, -16, v4
	v_add_u32_e32 v4, v3, v4
	s_add_u32 s8, s58, 0xaa00000
	v_and_b32_e32 v3, 3, v3
	v_lshrrev_b32_e32 v5, 2, v4
	v_lshlrev_b32_e32 v6, 1, v4
	s_mul_i32 s13, s10, s12
	s_addc_u32 s9, s59, 0
	v_and_or_b32 v3, v4, s4, v3
	v_and_b32_e32 v5, 4, v5
	v_and_b32_e32 v6, 24, v6
	s_abs_i32 s20, s13
	v_or3_b32 v3, v3, v5, v6
	v_cvt_f32_u32_e32 v5, s20
	v_and_b32_e32 v2, 0xc0, v2
	v_sub_u32_e32 v0, v0, v2
	v_lshlrev_b32_e32 v1, 5, v1
	v_rcp_iflag_f32_e32 v2, v5
	v_ashrrev_i16_sdwa v0, v244, sext(v0) dst_sel:DWORD dst_unused:UNUSED_PAD src0_sel:DWORD src1_sel:BYTE_0
	v_and_b32_e32 v1, 32, v1
	v_bfe_i32 v0, v0, 0, 16
	v_add_lshl_u32 v0, v1, v0, 1
	v_mul_f32_e32 v1, 0x4f7ffffe, v2
	v_cvt_u32_f32_e32 v1, v1
	s_sub_i32 s36, 0, s20
	s_ashr_i32 s21, s13, 31
	v_readlane_b32 s4, v254, 61
	v_readfirstlane_b32 s37, v1
	s_mul_i32 s36, s36, s37
	s_mul_hi_u32 s36, s37, s36
	s_xor_b32 s21, s4, s21
	s_add_i32 s37, s37, s36
	v_readlane_b32 s4, v254, 63
	s_mul_hi_u32 s36, s4, s37
	s_mul_i32 s37, s36, s20
	s_sub_i32 s37, s4, s37
	s_add_i32 s40, s36, 1
	s_sub_i32 s41, s37, s20
	s_cmp_ge_u32 s37, s20
	s_cselect_b32 s36, s40, s36
	s_cselect_b32 s37, s41, s37
	s_add_i32 s40, s36, 1
	s_cmp_ge_u32 s37, s20
	s_cselect_b32 s20, s40, s36
	s_abs_i32 s36, s11
	s_sub_i32 s40, 0, s36
	s_xor_b32 s20, s20, s21
	s_sub_i32 s20, s20, s21
	s_abs_i32 s37, s20
	s_xor_b32 s21, s20, s11
	s_ashr_i32 s21, s21, 31
	v_readlane_b32 s4, v254, 62
	v_lshl_add_u32 v214, v3, 9, v0
	v_lshlrev_b32_e32 v3, 2, v4
	s_mov_b32 s41, 0x20000000
	s_mul_hi_u32 s40, s37, s41
	s_mul_i32 s41, s40, s36
	s_sub_i32 s37, s37, s41
	s_add_i32 s41, s40, 1
	s_sub_i32 s42, s37, s36
	s_cmp_ge_u32 s37, s36
	s_cselect_b32 s40, s41, s40
	s_cselect_b32 s37, s42, s37
	s_add_i32 s41, s40, 1
	s_cmp_ge_u32 s37, s36
	s_cselect_b32 s36, s41, s40
	s_lshl_b32 s12, s12, 2
	s_abs_i32 s37, s12
	s_xor_b32 s36, s36, s21
	s_sub_i32 s50, s36, s21
	s_mul_i32 s11, s50, s11
	s_sub_i32 s21, 0, s37
	s_sub_i32 s52, s20, s11
	s_mul_i32 s20, s20, s13
	s_sub_i32 s11, s4, s20
	s_abs_i32 s20, s11
	s_xor_b32 s13, s11, s12
	s_mov_b32 s36, 0x40000000
	s_mul_hi_u32 s21, s20, s36
	s_mul_i32 s36, s21, s37
	s_sub_i32 s20, s20, s36
	s_ashr_i32 s13, s13, 31
	s_add_i32 s36, s21, 1
	s_sub_i32 s40, s20, s37
	s_cmp_ge_u32 s20, s37
	s_cselect_b32 s21, s36, s21
	s_cselect_b32 s20, s40, s20
	s_add_i32 s36, s21, 1
	s_cmp_ge_u32 s20, s37
	s_cselect_b32 s20, s36, s21
	s_xor_b32 s20, s20, s13
	s_sub_i32 s13, s20, s13
	s_lshl_b32 s20, s13, 2
	s_sub_i32 s10, s10, s20
	s_min_i32 s21, s10, 4
	s_abs_i32 s10, s21
	v_cvt_f32_u32_e32 v1, s10
	v_and_b32_e32 v2, 0x7fffc0, v4
	v_and_b32_e32 v3, 60, v3
	v_bfe_u32 v4, v4, 4, 2
	v_or3_b32 v2, v2, v3, v4
	v_lshl_add_u32 v216, v2, 9, v0
	v_rcp_iflag_f32_e32 v0, v1
	s_sub_i32 s36, 0, s10
	s_mul_i32 s13, s13, s12
	s_sub_i32 s12, s11, s13
	v_mul_f32_e32 v0, 0x4f7ffffe, v0
	v_cvt_u32_f32_e32 v0, v0
	s_abs_i32 s13, s12
	s_xor_b32 s11, s12, s21
	s_ashr_i32 s11, s11, 31
	v_readfirstlane_b32 s37, v0
	s_mul_i32 s36, s36, s37
	s_mul_hi_u32 s36, s37, s36
	s_add_i32 s37, s37, s36
	s_mul_hi_u32 s36, s13, s37
	s_mul_i32 s37, s36, s10
	s_sub_i32 s13, s13, s37
	s_add_i32 s37, s36, 1
	s_sub_i32 s40, s13, s10
	s_cmp_ge_u32 s13, s10
	s_cselect_b32 s36, s37, s36
	s_cselect_b32 s13, s40, s13
	s_add_i32 s37, s36, 1
	s_cmp_ge_u32 s13, s10
	s_cselect_b32 s10, s37, s36
	s_xor_b32 s10, s10, s11
	s_sub_i32 s10, s10, s11
	s_mul_i32 s13, s10, s21
	s_sub_i32 s12, s12, s13
	s_add_i32 s12, s12, s20
	s_ashr_i32 s53, s52, 31
	s_ashr_i32 s11, s10, 31
	s_ashr_i32 s13, s12, 31
	s_ashr_i32 s51, s50, 31
	s_lshl_b64 s[20:21], s[52:53], 17
	s_add_u32 s40, s8, s20
	s_addc_u32 s41, s9, s21
	s_lshl_b64 s[36:37], s[50:51], 20
	s_add_u32 s36, s56, s36
	s_addc_u32 s37, s57, s37
	s_add_u32 s20, s36, s20
	s_addc_u32 s21, s37, s21
	s_lshl_b64 s[10:11], s[10:11], 17
	s_add_u32 s76, s20, s10
	s_addc_u32 s77, s21, s11
	s_add_i32 s51, s29, 0
	s_add_i32 m0, s51, 0x10000
	v_mov_b32_e32 v215, v193
	global_load_lds_dwordx4 v214, s[76:77]
	s_add_i32 m0, s51, 0x12000
	s_add_u32 s10, s76, 0x10000
	global_load_lds_dwordx4 v210, s[76:77]
	s_addc_u32 s11, s77, 0
	s_add_i32 m0, s51, 0x14000
	v_mov_b32_e32 v211, v193
	global_load_lds_dwordx4 v214, s[10:11]
	s_add_i32 m0, s51, 0x16000
	v_mov_b32_e32 v217, v193
	global_load_lds_dwordx4 v210, s[10:11]
	s_lshl_b64 s[10:11], s[12:13], 17
	s_add_u32 s60, s40, s10
	s_addc_u32 s61, s41, s11
	s_add_i32 s53, s51, 0x2000
	s_mov_b32 m0, s51
	s_add_u32 s10, s60, 0x10000
	global_load_lds_dwordx4 v216, s[60:61]
	s_mov_b32 m0, s53
	s_addc_u32 s11, s61, 0
	s_add_i32 s62, s51, 0x4000
	global_load_lds_dwordx4 v212, s[60:61]
	s_mov_b32 m0, s62
	s_add_i32 s68, s51, 0x6000
	global_load_lds_dwordx4 v216, s[10:11]
	s_mov_b32 m0, s68
	v_mov_b32_e32 v213, v193
	global_load_lds_dwordx4 v212, s[10:11]
	s_load_dwordx2 s[10:11], s[30:31], 0x60
	v_lshl_add_u64 v[6:7], s[76:77], 0, v[214:215]
	v_lshl_add_u64 v[4:5], s[76:77], 0, v[210:211]
	v_lshl_add_u64 v[2:3], s[60:61], 0, v[216:217]
	s_and_b64 vcc, exec, s[38:39]
	v_lshl_add_u64 v[0:1], s[60:61], 0, v[212:213]
	s_cbranch_vccnz .LBB0_501
	s_barrier

;     __device__ __forceinline__ bool next(int i, Unit& u) const {
;         int nM = this->nM, nN = this->nN, Z2 = this->Z2; asm volatile("" : "+s"(nM), "+s"(nN), "+s"(Z2));
;         const long L = (long)i * G + c; if (L >= nwg) return false;
;         int wgid = (int)L; { const int q = nwg / NXCD, r = nwg % NXCD, xcd = wgid % NXCD, off = wgid / NXCD; wgid = (xcd < r ? xcd * (q + 1) : r * (q + 1) + (xcd - r) * q) + off; }
;         if (rev) wgid = nwg - 1 - wgid;
;         const int per = nM * nN, z = wgid / per, rem = wgid - z * per;
;         const int nig = WGM * nN, gid = rem / nig, fm = gid * WGM, gsz = (nM - fm) < WGM ? (nM - fm) : WGM, ri = rem - gid * nig;
;         u.pm = fm + (ri % gsz); u.pn = ri / gsz; u.z1 = z / Z2; u.z2 = z - u.z1 * Z2; return true;
; template <class Epi>
; __device__ __forceinline__ void gemm_phase(PG8_LAS unsigned char* lds, PG8_LAS unsigned char* xl, const Gemm g, const Sched& S, const Epi& E, const int wid) {
;     ...
;         const bool has_next = S.next(ui + 1, nxt);
.LBB0_504:
	v_cmp_gt_i64_e32 vcc, s[20:21], v[202:203]
	s_mov_b32 s10, 8
	s_mov_b32 s11, 1
	s_mov_b32 s12, 1
	v_cmp_lt_i64_e64 s[48:49], s[20:21], v[200:201]
	s_cbranch_vccnz .LBB0_506
	s_ashr_i32 s13, s20, 31
	s_lshr_b32 s13, s13, 29
	s_add_i32 s13, s20, s13
	s_ashr_i32 s30, s13, 3
	s_and_b32 s13, s13, -8
	s_sub_i32 s13, s20, s13
	s_cmp_lt_i32 s13, 0
	s_movk_i32 s4, 0xa1
	s_mul_i32 s36, s11, s12
	s_cselect_b32 s31, s4, 0xa0
	s_abs_i32 s37, s36
	s_mul_i32 s13, s13, s31
	s_sub_i32 s31, 0, s37
	s_add_i32 s13, s13, s30
	s_abs_i32 s40, s13
	s_xor_b32 s30, s13, s36
	s_ashr_i32 s30, s30, 31
	s_mov_b32 s41, 0xffffffff
	s_mul_hi_u32 s31, s40, s41
	s_mul_i32 s41, s31, s37
	s_sub_i32 s40, s40, s41
	s_add_i32 s41, s31, 1
	s_sub_i32 s42, s40, s37
	s_cmp_ge_u32 s40, s37
	s_cselect_b32 s31, s41, s31
	s_cselect_b32 s40, s42, s40
	s_add_i32 s41, s31, 1
	s_cmp_ge_u32 s40, s37
	s_cselect_b32 s31, s41, s31
	s_lshl_b32 s12, s12, 2
	s_abs_i32 s37, s12
	s_xor_b32 s31, s31, s30
	s_sub_i32 s31, s31, s30
	s_sub_i32 s40, 0, s37
	s_mul_i32 s30, s31, s36
	s_sub_i32 s13, s13, s30
	s_abs_i32 s36, s13
	s_xor_b32 s30, s13, s12
	s_ashr_i32 s30, s30, 31
	s_mov_b32 s41, 0x40000000
	s_mul_hi_u32 s40, s36, s41
	s_mul_i32 s41, s40, s37
	s_sub_i32 s36, s36, s41
	s_add_i32 s41, s40, 1
	s_sub_i32 s42, s36, s37
	s_cmp_ge_u32 s36, s37
	s_cselect_b32 s40, s41, s40
	s_cselect_b32 s36, s42, s36
	s_add_i32 s41, s40, 1
	s_cmp_ge_u32 s36, s37
	s_cselect_b32 s36, s41, s40
	s_xor_b32 s36, s36, s30
	s_sub_i32 s30, s36, s30
	s_lshl_b32 s36, s30, 2
	s_sub_i32 s11, s11, s36
	s_min_i32 s11, s11, 4
	s_abs_i32 s37, s11
	v_cvt_f32_u32_e32 v0, s37
	s_sub_i32 s40, 0, s37
	s_mul_i32 s30, s30, s12
	s_sub_i32 s12, s13, s30
	v_rcp_iflag_f32_e32 v0, v0
	s_abs_i32 s30, s12
	s_xor_b32 s13, s12, s11
	s_ashr_i32 s13, s13, 31
	v_mul_f32_e32 v0, 0x4f7ffffe, v0
	v_cvt_u32_f32_e32 v0, v0
	s_nop 0
	v_readfirstlane_b32 s41, v0
	s_mul_i32 s40, s40, s41
	s_mul_hi_u32 s40, s41, s40
	s_add_i32 s41, s41, s40
	s_mul_hi_u32 s40, s30, s41
	s_mul_i32 s41, s40, s37
	s_sub_i32 s30, s30, s41
	s_add_i32 s41, s40, 1
	s_sub_i32 s42, s30, s37
	s_cmp_ge_u32 s30, s37
	s_cselect_b32 s40, s41, s40
	s_cselect_b32 s30, s42, s30
	s_add_i32 s41, s40, 1
	s_cmp_ge_u32 s30, s37
	s_cselect_b32 s30, s41, s40
	s_abs_i32 s37, s10
	s_xor_b32 s30, s30, s13
	s_sub_i32 s30, s30, s13
	s_sub_i32 s13, 0, s37
	s_mul_i32 s11, s30, s11
	s_sub_i32 s11, s12, s11
	s_abs_i32 s12, s31
	s_add_i32 s36, s36, s11
	s_xor_b32 s11, s31, s10
	s_ashr_i32 s11, s11, 31
	s_mov_b32 s40, 0x20000000
	s_mul_hi_u32 s13, s12, s40
	s_mul_i32 s40, s13, s37
	s_sub_i32 s12, s12, s40
	s_add_i32 s40, s13, 1
	s_sub_i32 s41, s12, s37
	s_cmp_ge_u32 s12, s37
	s_cselect_b32 s13, s40, s13
	s_cselect_b32 s12, s41, s12
	s_add_i32 s40, s13, 1
	s_cmp_ge_u32 s12, s37
	s_cselect_b32 s12, s40, s13
	s_xor_b32 s12, s12, s11
	s_sub_i32 s40, s12, s11
	s_mul_i32 s10, s40, s10
	s_sub_i32 s42, s31, s10

;     __device__ __forceinline__ bool next(int i, Unit& u) const {
;     ...
;         const long L = (long)i * G + c; if (L >= nwg) return false;
;         int wgid = (int)L; { const int q = nwg / NXCD, r = nwg % NXCD, xcd = wgid % NXCD, off = wgid / NXCD; wgid = (xcd < r ? xcd * (q + 1) : r * (q + 1) + (xcd - r) * q) + off; }
;         if (rev) wgid = nwg - 1 - wgid;
;         const int per = nM * nN, z = wgid / per, rem = wgid - z * per;
;         const int nig = WGM * nN, gid = rem / nig, fm = gid * WGM, gsz = (nM - fm) < WGM ? (nM - fm) : WGM, ri = rem - gid * nig;
;         u.pm = fm + (ri % gsz); u.pn = ri / gsz; u.z1 = z / Z2; u.z2 = z - u.z1 * Z2; return true;
; template <class Epi>
; __device__ __forceinline__ void gemm_phase(PG8_LAS unsigned char* lds, PG8_LAS unsigned char* xl, const Gemm g, const Sched& S, const Epi& E, const int wid) {
;     ...
;     if (!S.next(0, cur)) return;
.LBB0_516:
	v_readlane_b32 s4, v254, 36
	v_readlane_b32 s5, v254, 37
	s_mov_b32 s10, 1
	s_movk_i32 s8, 0xa0
	v_cndmask_b32_e64 v0, 0, 1, s[4:5]
	s_mov_b32 s9, 16
	v_cmp_ne_u32_e64 s[46:47], 1, v0
	s_andn2_b64 vcc, exec, s[4:5]
	v_mbcnt_lo_u32_b32 v8, -1, 0
	v_mbcnt_hi_u32_b32 v8, -1, v8
	s_cbranch_vccnz .LBB0_518
	s_mul_i32 s10, s8, s9
	s_abs_i32 s10, s10
	s_sub_i32 s11, 0, s10
	v_readlane_b32 s4, v254, 51
	s_nop 0
	s_mov_b32 s12, 0x199999
	s_mul_hi_u32 s11, s4, s12
	s_mul_i32 s11, s11, s10
	s_sub_i32 s11, s4, s11
	s_sub_i32 s12, s11, s10
	s_cmp_ge_u32 s11, s10
	s_cselect_b32 s11, s12, s11
	s_sub_i32 s12, s11, s10
	s_cmp_ge_u32 s11, s10
	s_cselect_b32 s10, s12, s11
	s_lshl_b32 s9, s9, 2
	s_abs_i32 s11, s9
	v_readlane_b32 s4, v254, 50
	s_sub_i32 s12, 0, s11
	s_xor_b32 s10, s10, s4
	s_sub_i32 s10, s10, s4
	s_abs_i32 s20, s10
	s_xor_b32 s13, s10, s9
	s_ashr_i32 s13, s13, 31
	s_mov_b32 s21, 0x4000000
	s_mul_hi_u32 s12, s20, s21
	s_mul_i32 s21, s12, s11
	s_sub_i32 s20, s20, s21
	s_add_i32 s30, s12, 1
	s_sub_i32 s21, s20, s11
	s_cmp_ge_u32 s20, s11
	s_cselect_b32 s12, s30, s12
	s_cselect_b32 s20, s21, s20
	s_add_i32 s21, s12, 1
	s_cmp_ge_u32 s20, s11
	s_cselect_b32 s11, s21, s12
	s_xor_b32 s11, s11, s13
	s_sub_i32 s11, s11, s13
	s_lshl_b32 s12, s11, 2
	s_sub_i32 s8, s8, s12
	s_min_i32 s8, s8, 4
	s_abs_i32 s13, s8
	s_sub_i32 s20, 0, s13
	s_mul_i32 s11, s11, s9
	s_sub_i32 s9, s10, s11
	s_abs_i32 s10, s9
	s_xor_b32 s11, s9, s8
	s_ashr_i32 s11, s11, 31
	s_mov_b32 s21, 0x40000000
	s_mul_hi_u32 s20, s10, s21
	s_mul_i32 s21, s20, s13
	s_sub_i32 s10, s10, s21
	s_add_i32 s30, s20, 1
	s_sub_i32 s21, s10, s13
	s_cmp_ge_u32 s10, s13
	s_cselect_b32 s20, s30, s20
	s_cselect_b32 s10, s21, s10
	s_add_i32 s21, s20, 1
	s_cmp_ge_u32 s10, s13
	s_cselect_b32 s10, s21, s20
	s_xor_b32 s10, s10, s11
	s_sub_i32 s44, s10, s11
	s_mul_i32 s8, s44, s8
	s_sub_i32 s8, s9, s8
	s_add_i32 s40, s12, s8

;     __device__ __forceinline__ bool next(int i, Unit& u) const {
;     ...
;         const long L = (long)i * G + c; if (L >= nwg) return false;
;         int wgid = (int)L; { const int q = nwg / NXCD, r = nwg % NXCD, xcd = wgid % NXCD, off = wgid / NXCD; wgid = (xcd < r ? xcd * (q + 1) : r * (q + 1) + (xcd - r) * q) + off; }
;         if (rev) wgid = nwg - 1 - wgid;
;         const int per = nM * nN, z = wgid / per, rem = wgid - z * per;
;         const int nig = WGM * nN, gid = rem / nig, fm = gid * WGM, gsz = (nM - fm) < WGM ? (nM - fm) : WGM, ri = rem - gid * nig;
;         u.pm = fm + (ri % gsz); u.pn = ri / gsz; u.z1 = z / Z2; u.z2 = z - u.z1 * Z2; return true;
.LBB0_524:
	s_mov_b32 s10, 1
	s_movk_i32 s8, 0xa0
	s_mov_b32 s9, 16
	s_add_i32 s95, s95, 1
	s_mul_i32 s10, s95, s94
	s_mul_hi_u32 s11, s95, s87
	s_add_i32 s11, s11, s10
	s_mul_i32 s10, s95, s87
	s_add_u32 s10, s10, s2
	s_addc_u32 s11, s11, s33
	v_mov_b64_e32 v[0:1], 0xa00
	v_cmp_lt_i64_e64 s[46:47], s[10:11], v[0:1]
	v_mov_b64_e32 v[0:1], 0x9ff
	v_cmp_gt_i64_e64 s[48:49], s[10:11], v[0:1]
	s_and_b64 vcc, exec, s[48:49]
	s_cbranch_vccnz .LBB0_526
	s_ashr_i32 s11, s10, 31
	s_lshr_b32 s11, s11, 29
	s_add_i32 s11, s10, s11
	s_ashr_i32 s30, s11, 3
	s_and_b32 s11, s11, -8
	s_sub_i32 s10, s10, s11
	s_cmp_lt_i32 s10, 0
	s_mul_i32 s31, s8, s9
	s_cselect_b32 s11, s4, 0x140
	s_abs_i32 s31, s31
	s_mul_i32 s10, s10, s11
	s_sub_i32 s11, 0, s31
	s_add_i32 s10, s10, s30
	s_ashr_i32 s30, s10, 31
	s_abs_i32 s10, s10
	s_mov_b32 s36, 0x199999
	s_mul_hi_u32 s11, s10, s36
	s_mul_i32 s11, s11, s31
	s_sub_i32 s10, s10, s11
	s_sub_i32 s11, s10, s31
	s_cmp_ge_u32 s10, s31
	s_cselect_b32 s10, s11, s10
	s_sub_i32 s11, s10, s31
	s_cmp_ge_u32 s10, s31
	s_cselect_b32 s10, s11, s10
	s_lshl_b32 s9, s9, 2
	s_abs_i32 s11, s9
	s_xor_b32 s10, s10, s30
	s_sub_i32 s10, s10, s30
	s_sub_i32 s30, 0, s11
	s_abs_i32 s36, s10
	s_xor_b32 s31, s10, s9
	s_ashr_i32 s31, s31, 31
	s_mov_b32 s37, 0x4000000
	s_mul_hi_u32 s30, s36, s37
	s_mul_i32 s37, s30, s11
	s_sub_i32 s36, s36, s37
	s_add_i32 s42, s30, 1
	s_sub_i32 s37, s36, s11
	s_cmp_ge_u32 s36, s11
	s_cselect_b32 s30, s42, s30
	s_cselect_b32 s36, s37, s36
	s_add_i32 s37, s30, 1
	s_cmp_ge_u32 s36, s11
	s_cselect_b32 s11, s37, s30
	s_xor_b32 s11, s11, s31
	s_sub_i32 s11, s11, s31
	s_lshl_b32 s30, s11, 2
	s_sub_i32 s8, s8, s30
	s_min_i32 s8, s8, 4
	s_abs_i32 s31, s8
	s_sub_i32 s36, 0, s31
	s_mul_i32 s11, s11, s9
	s_sub_i32 s9, s10, s11
	s_abs_i32 s10, s9
	s_xor_b32 s11, s9, s8
	s_ashr_i32 s11, s11, 31
	s_mov_b32 s37, 0x40000000
	s_mul_hi_u32 s36, s10, s37
	s_mul_i32 s37, s36, s31
	s_sub_i32 s10, s10, s37
	s_add_i32 s42, s36, 1
	s_sub_i32 s37, s10, s31
	s_cmp_ge_u32 s10, s31
	s_cselect_b32 s36, s42, s36
	s_cselect_b32 s10, s37, s10
	s_add_i32 s37, s36, 1
	s_cmp_ge_u32 s10, s31
	s_cselect_b32 s10, s37, s36
	s_xor_b32 s10, s10, s11
	s_sub_i32 s58, s10, s11
	s_mul_i32 s8, s58, s8
	s_sub_i32 s8, s9, s8
	s_add_i32 s36, s30, s8

; __device__ __forceinline__ const char* a_tile(const Gemm& g, const Unit& u) { return (const char*)(g.A + ((long)u.z1 * g.aS1 + (long)u.z2 * g.aS2 + (long)u.pm * BM * g.lda)); }
; __device__ __forceinline__ const char* b_tile(const Gemm& g, const Unit& u) { return (const char*)(g.Bt + ((long)u.z1 * g.bS1 + (long)u.z2 * g.bS2 + (long)u.pn * BM * g.ldb)); }
; #define PG8_WAIT_V(n) asm volatile("s_waitcnt vmcnt(" #n ")" ::: "memory")
; template <class Epi>
; __device__ __forceinline__ void gemm_phase(PG8_LAS unsigned char* lds, PG8_LAS unsigned char* xl, const Gemm g, const Sched& S, const Epi& E, const int wid) {
;     ...
;     for (int i = 0; i < 2; ++i) { int R, C; stage_rc(tid * 16 + i * 8192, R, C); const int Rb = Epi::PERM ? ((R & ~31) + perm32(R & 31)) : R;
;         const int Ra = Epi::PERM ? ((R & ~63) + 4 * (R & 15) + ((R >> 4) & 3)) : R;
;         voffA[i] = (unsigned)(Ra * g.lda + C) * 2u; voffB[i] = (unsigned)(Rb * g.ldb + C) * 2u; }
;     const size_t kstep = (size_t)(BK * 2);
;     const size_t hstepA = (size_t)HALF * g.lda * 2, hstepB = (size_t)HALF * g.ldb * 2;
;     const unsigned ldsw = (unsigned)wid * 1024u;
;     const int aoff = lds_byte(wr * 64 + fr, fq * 8), boff = lds_byte(wc * 32 + fr, fq * 8);
;     ...
;     Unit cur, nxt; int ui = 0;
;     if (!S.next(0, cur)) return;
;     Acc acc;
; #pragma unroll
;     for (int a = 0; a < 2; ++a)
; #pragma unroll
;         for (int b = 0; b < 2; ++b)
; #pragma unroll
;             for (int m = 0; m < 4; ++m)
; #pragma unroll
;                 for (int n = 0; n < 2; ++n) acc[a][b][m][n] = (f32x4){0.f, 0.f, 0.f, 0.f};
;     bf16x8 At[4][2], B0[2][2], B1[2][2];
;     float prc[8];
; #pragma unroll
;     for (int k = 0; k < 8; ++k) prc[k] = 1.0f;
;     if constexpr (Epi::PRE) { const float* pb = E.pre_base(cur) + wr * 64 + 4 * fr;
; #pragma unroll
;         for (int k = 0; k < 8; ++k) prc[k] = pb[(k >> 2) * HALF + (k & 3)]; }
;     const char* cA = a_tile(g, cur); const char* cB = b_tile(g, cur);
;     PG8_STAGE(PG8_SB(0, 0), cB, voffB); PG8_STAGE(PG8_SB(0, 1), cB + hstepB, voffB); PG8_STAGE(PG8_SA(0, 0), cA, voffA); PG8_STAGE(PG8_SA(0, 1), cA + hstepA, voffA);
;     if (wr == 1) PG8_BAR;
;     PG8_WAIT_V(2); PG8_BAR;
;     PG8_STAGE(PG8_SB(1, 0), cB + kstep, voffB); PG8_STAGE(PG8_SA(1, 0), cA + kstep, voffA); PG8_STAGE(PG8_SB(1, 1), cB + hstepB + kstep, voffB);
;     PG8_WAIT_V(6); PG8_BAR;
.LBB0_678:
	v_readlane_b32 s4, v252, 46
	v_readlane_b32 s8, v253, 0
	v_readlane_b32 s5, v252, 47
	v_readlane_b32 s9, v253, 1
	v_readlane_b32 s0, v252, 41
	s_mov_b32 s11, 8
	s_mov_b32 s1, 1
	s_movk_i32 s10, 0xa0
	s_and_b64 vcc, exec, s[4:5]
	s_waitcnt lgkmcnt(0)
	s_barrier
	v_mbcnt_lo_u32_b32 v15, -1, 0
	v_mbcnt_hi_u32_b32 v15, -1, v15
	s_cbranch_vccnz .LBB0_698
	v_lshlrev_b32_e32 v17, 4, v15
	v_add_u32_e32 v0, s29, v17
	v_add_u32_e32 v1, 0x2000, v0
	v_ashrrev_i32_e32 v2, 31, v1
	v_lshrrev_b32_e32 v2, 22, v2
	v_add_u32_e32 v2, v1, v2
	v_ashrrev_i32_e32 v2, 10, v2
	v_mul_i32_i24_e32 v3, 0x400, v2
	v_sub_u32_e32 v1, v1, v3
	v_lshrrev_b32_e32 v3, 4, v1
	v_bitop3_b32 v1, v3, v1, 32 bitop3:0x6c
	v_ashrrev_i32_e32 v3, 31, v1
	v_lshrrev_b32_e32 v3, 26, v3
	v_add_u32_e32 v3, v1, v3
	v_lshlrev_b32_e32 v5, 3, v2
	v_lshlrev_b32_e32 v2, 5, v2
	v_and_b32_e32 v8, 32, v2
	v_and_b32_e32 v2, 0xffc0, v3
	v_sub_u32_e32 v1, v1, v2
	v_lshrrev_b16_e32 v2, 7, v1
	v_and_b32_e32 v2, 1, v2
	v_ashrrev_i32_e32 v4, 6, v3
	v_and_b32_e32 v5, -16, v5
	v_add_u16_e32 v1, v1, v2
	v_add_u32_e32 v5, v4, v5
	v_ashrrev_i16_sdwa v1, v244, sext(v1) dst_sel:DWORD dst_unused:UNUSED_PAD src0_sel:DWORD src1_sel:BYTE_0
	v_and_b32_e32 v4, 3, v4
	s_mov_b32 s4, 0xfffe0
	v_lshrrev_b32_e32 v6, 2, v5
	v_lshlrev_b32_e32 v7, 1, v5
	v_bfe_i32 v9, v1, 0, 16
	v_and_or_b32 v4, v5, s4, v4
	v_and_b32_e32 v6, 4, v6
	v_and_b32_e32 v7, 24, v7
	v_add_u32_e32 v1, v8, v9
	v_or3_b32 v4, v4, v6, v7
	v_lshlrev_b32_e32 v2, 1, v1
	s_load_dwordx2 s[12:13], s[8:9], 0xd8
	v_lshl_add_u32 v152, v4, 12, v2
	v_lshlrev_b32_e32 v2, 2, v5
	v_and_b32_e32 v10, 0x7fffffc0, v5
	v_and_b32_e32 v11, 60, v2
	v_bfe_u32 v12, v5, 4, 2
	v_or3_b32 v2, v10, v11, v12
	v_mul_lo_u32 v2, v2, s17
	v_add_lshl_u32 v154, v2, v1, 1
	v_ashrrev_i32_e32 v1, 31, v0
	s_waitcnt lgkmcnt(0)
	s_add_u32 s1, s12, 0x27800000
	v_lshrrev_b32_e32 v1, 22, v1
	s_addc_u32 s8, s13, 0
	v_add_u32_e32 v1, v0, v1
	s_add_u32 s9, s12, 0x3000000
	v_ashrrev_i32_e32 v1, 10, v1
	s_mul_i32 s20, s10, s11
	s_addc_u32 s52, s13, 0
	v_mul_i32_i24_e32 v2, 0x400, v1
	v_lshlrev_b32_e32 v4, 3, v1
	v_lshlrev_b32_e32 v1, 5, v1
	s_abs_i32 s20, s20
	v_and_b32_e32 v13, 32, v1
	v_sub_u32_e32 v0, v0, v2
	v_lshrrev_b32_e32 v2, 4, v0
	v_bitop3_b32 v0, v2, v0, 32 bitop3:0x6c
	v_ashrrev_i32_e32 v2, 31, v0
	v_lshrrev_b32_e32 v2, 26, v2
	v_add_u32_e32 v2, v0, v2
	s_sub_i32 s21, 0, s20
	v_ashrrev_i32_e32 v3, 6, v2
	v_and_b32_e32 v4, -16, v4
	s_mov_b32 s30, 0x333333
	s_mul_i32 s21, s21, s30
	v_add_u32_e32 v4, v3, v4
	v_and_b32_e32 v3, 3, v3
	s_mul_hi_u32 s21, s30, s21
	v_and_or_b32 v3, v4, s4, v3
	s_add_i32 s30, s30, s21
	v_readlane_b32 s4, v254, 53
	s_mul_hi_u32 s21, s4, s30
	s_mul_i32 s21, s21, s20
	s_sub_i32 s21, s4, s21
	s_sub_i32 s30, s21, s20
	s_cmp_ge_u32 s21, s20
	s_cselect_b32 s21, s30, s21
	s_sub_i32 s30, s21, s20
	s_cmp_ge_u32 s21, s20
	s_cselect_b32 s20, s30, s21
	s_lshl_b32 s11, s11, 2
	s_abs_i32 s21, s11
	v_readlane_b32 s4, v254, 52
	s_sub_i32 s36, 0, s21
	s_xor_b32 s20, s20, s4
	s_sub_i32 s20, s20, s4
	s_abs_i32 s31, s20
	s_xor_b32 s30, s20, s11
	s_ashr_i32 s30, s30, 31
	v_and_b32_e32 v2, 0xc0, v2
	v_sub_u32_e32 v0, v0, v2
	s_mov_b32 s37, 0x8000000
	s_mul_hi_u32 s36, s31, s37
	s_mul_i32 s37, s36, s21
	s_sub_i32 s31, s31, s37
	s_add_i32 s37, s36, 1
	s_sub_i32 s40, s31, s21
	s_cmp_ge_u32 s31, s21
	s_cselect_b32 s36, s37, s36
	s_cselect_b32 s31, s40, s31
	s_add_i32 s37, s36, 1
	s_cmp_ge_u32 s31, s21
	s_cselect_b32 s21, s37, s36
	s_xor_b32 s21, s21, s30
	s_sub_i32 s21, s21, s30
	v_ashrrev_i16_sdwa v0, v244, sext(v0) dst_sel:DWORD dst_unused:UNUSED_PAD src0_sel:DWORD src1_sel:BYTE_0
	s_lshl_b32 s30, s21, 2
	v_lshrrev_b32_e32 v5, 2, v4
	v_lshlrev_b32_e32 v6, 1, v4
	v_bfe_i32 v14, v0, 0, 16
	s_sub_i32 s10, s10, s30
	v_and_b32_e32 v5, 4, v5
	v_and_b32_e32 v6, 24, v6
	v_add_u32_e32 v0, v13, v14
	s_min_i32 s10, s10, 4
	v_or3_b32 v3, v3, v5, v6
	v_lshlrev_b32_e32 v2, 1, v0
	s_abs_i32 s31, s10
	v_lshl_add_u32 v156, v3, 12, v2
	v_lshlrev_b32_e32 v2, 2, v4
	v_cvt_f32_u32_e32 v1, s31
	v_and_b32_e32 v16, 0x7fffffc0, v4
	v_and_b32_e32 v18, 60, v2
	v_bfe_u32 v19, v4, 4, 2
	v_or3_b32 v2, v16, v18, v19
	v_mul_lo_u32 v2, v2, s17
	v_add_lshl_u32 v158, v2, v0, 1
	v_rcp_iflag_f32_e32 v0, v1
	s_sub_i32 s36, 0, s31
	s_mul_i32 s21, s21, s11
	s_sub_i32 s11, s20, s21
	v_mul_f32_e32 v0, 0x4f7ffffe, v0
	v_cvt_u32_f32_e32 v0, v0
	s_abs_i32 s21, s11
	s_xor_b32 s20, s11, s10
	s_ashr_i32 s20, s20, 31
	v_readfirstlane_b32 s37, v0
	s_mul_i32 s36, s36, s37
	s_mul_hi_u32 s36, s37, s36
	s_add_i32 s37, s37, s36
	s_mul_hi_u32 s36, s21, s37
	s_mul_i32 s37, s36, s31
	s_sub_i32 s21, s21, s37
	s_add_i32 s37, s36, 1
	s_sub_i32 s40, s21, s31
	s_cmp_ge_u32 s21, s31
	s_cselect_b32 s36, s37, s36
	s_cselect_b32 s21, s40, s21
	s_add_i32 s37, s36, 1
	s_cmp_ge_u32 s21, s31
	s_cselect_b32 s21, s37, s36
	s_xor_b32 s21, s21, s20
	s_sub_i32 s40, s21, s20
	s_mul_i32 s10, s40, s10
	s_sub_i32 s10, s11, s10
	s_ashr_i32 s41, s40, 31
	s_add_i32 s66, s30, s10
	s_lshl_b64 s[10:11], s[40:41], 20
	s_add_u32 s44, s9, s10
	s_addc_u32 s45, s52, s11
	s_add_i32 s53, s29, 0
	s_add_i32 m0, s53, 0x10000
	v_mov_b32_e32 v157, v193
	global_load_lds_dwordx4 v156, s[44:45]
	s_add_i32 m0, s53, 0x12000
	s_add_u32 s10, s44, 0x80000
	global_load_lds_dwordx4 v152, s[44:45]
	s_addc_u32 s11, s45, 0
	s_add_i32 m0, s53, 0x14000
	v_mov_b32_e32 v153, v193
	global_load_lds_dwordx4 v156, s[10:11]
	s_add_i32 m0, s53, 0x16000
	v_mov_b32_e32 v159, v193
	global_load_lds_dwordx4 v152, s[10:11]
	s_mul_i32 s11, s66, 0x580000
	s_mul_hi_i32 s10, s66, 0x580000
	s_add_u32 s36, s1, s11
	s_addc_u32 s37, s8, s10
	s_add_i32 s56, s53, 0x2000
	s_mov_b32 m0, s53
	s_add_u32 s10, s36, 0x2c0000
	global_load_lds_dwordx4 v158, s[36:37]
	s_mov_b32 m0, s56
	s_addc_u32 s11, s37, 0
	s_add_i32 s57, s53, 0x4000
	global_load_lds_dwordx4 v154, s[36:37]
	s_mov_b32 m0, s57
	s_add_i32 s58, s53, 0x6000
	global_load_lds_dwordx4 v158, s[10:11]
	s_mov_b32 m0, s58
	v_mov_b32_e32 v155, v193
	global_load_lds_dwordx4 v154, s[10:11]
	v_lshl_add_u64 v[6:7], s[44:45], 0, v[156:157]
	v_lshl_add_u64 v[4:5], s[44:45], 0, v[152:153]
	v_lshl_add_u64 v[2:3], s[36:37], 0, v[158:159]
	s_and_b64 vcc, exec, s[38:39]
	v_lshl_add_u64 v[0:1], s[36:37], 0, v[154:155]
	s_cbranch_vccnz .LBB0_681
	s_barrier

;     __device__ __forceinline__ bool next(int i, Unit& u) const {
;     ...
;         const long L = (long)i * G + c; if (L >= nwg) return false;
;         int wgid = (int)L; { const int q = nwg / NXCD, r = nwg % NXCD, xcd = wgid % NXCD, off = wgid / NXCD; wgid = (xcd < r ? xcd * (q + 1) : r * (q + 1) + (xcd - r) * q) + off; }
;         if (rev) wgid = nwg - 1 - wgid;
;         const int per = nM * nN, z = wgid / per, rem = wgid - z * per;
;         const int nig = WGM * nN, gid = rem / nig, fm = gid * WGM, gsz = (nM - fm) < WGM ? (nM - fm) : WGM, ri = rem - gid * nig;
;         u.pm = fm + (ri % gsz); u.pn = ri / gsz; u.z1 = z / Z2; u.z2 = z - u.z1 * Z2; return true;
.LBB0_684:
	s_mov_b32 s20, 8
	s_mov_b32 s10, 1
	s_movk_i32 s13, 0xa0
	s_add_i32 s88, s88, 1
	s_mul_i32 s10, s88, s87
	s_mul_hi_u32 s11, s88, s0
	s_add_i32 s11, s11, s10
	s_mul_i32 s10, s88, s0
	s_add_u32 s10, s10, s2
	s_addc_u32 s11, s11, s33
	v_cmp_gt_i64_e32 vcc, s[10:11], v[202:203]
	v_cmp_lt_i64_e64 s[48:49], s[10:11], v[200:201]
	s_cbranch_vccnz .LBB0_686
	s_ashr_i32 s11, s10, 31
	s_lshr_b32 s11, s11, 29
	s_add_i32 s11, s10, s11
	s_and_b32 s12, s11, -8
	s_sub_i32 s10, s10, s12
	s_ashr_i32 s11, s11, 3
	s_cmp_lt_i32 s10, 0
	s_mul_i32 s21, s13, s20
	s_cselect_b32 s12, s4, 0xffffff60
	s_abs_i32 s21, s21
	s_mul_i32 s10, s10, s12
	s_sub_i32 s12, 0, s21
	s_sub_i32 s10, s10, s11
	s_addk_i32 s10, 0x4ff
	s_ashr_i32 s11, s10, 31
	s_abs_i32 s10, s10
	s_mov_b32 s30, 0x333333
	s_mul_hi_u32 s12, s10, s30
	s_mul_i32 s12, s12, s21
	s_sub_i32 s10, s10, s12
	s_sub_i32 s12, s10, s21
	s_cmp_ge_u32 s10, s21
	s_cselect_b32 s10, s12, s10
	s_sub_i32 s12, s10, s21
	s_cmp_ge_u32 s10, s21
	s_cselect_b32 s10, s12, s10
	s_lshl_b32 s12, s20, 2
	s_abs_i32 s20, s12
	s_xor_b32 s10, s10, s11
	s_sub_i32 s10, s10, s11
	s_sub_i32 s11, 0, s20
	s_abs_i32 s30, s10
	s_xor_b32 s21, s10, s12
	s_ashr_i32 s21, s21, 31
	s_mov_b32 s31, 0x8000000
	s_mul_hi_u32 s11, s30, s31
	s_mul_i32 s31, s11, s20
	s_sub_i32 s30, s30, s31
	s_add_i32 s41, s11, 1
	s_sub_i32 s31, s30, s20
	s_cmp_ge_u32 s30, s20
	s_cselect_b32 s11, s41, s11
	s_cselect_b32 s30, s31, s30
	s_add_i32 s31, s11, 1
	s_cmp_ge_u32 s30, s20
	s_cselect_b32 s11, s31, s11
	s_xor_b32 s11, s11, s21
	s_sub_i32 s11, s11, s21
	s_lshl_b32 s20, s11, 2
	s_sub_i32 s13, s13, s20
	s_min_i32 s13, s13, 4
	s_abs_i32 s21, s13
	s_sub_i32 s30, 0, s21
	s_mul_i32 s11, s11, s12
	s_sub_i32 s10, s10, s11
	s_abs_i32 s11, s10
	s_xor_b32 s12, s10, s13
	s_ashr_i32 s12, s12, 31
	s_mov_b32 s31, 0x40000000
	s_mul_hi_u32 s30, s11, s31
	s_mul_i32 s31, s30, s21
	s_sub_i32 s11, s11, s31
	s_add_i32 s41, s30, 1
	s_sub_i32 s31, s11, s21
	s_cmp_ge_u32 s11, s21
	s_cselect_b32 s30, s41, s30
	s_cselect_b32 s11, s31, s11
	s_add_i32 s31, s30, 1
	s_cmp_ge_u32 s11, s21
	s_cselect_b32 s11, s31, s30
	s_xor_b32 s11, s11, s12
	s_sub_i32 s12, s11, s12
	s_mul_i32 s11, s12, s13
	s_sub_i32 s10, s10, s11
	s_add_i32 s89, s20, s10

;     __device__ __forceinline__ bool next(int i, Unit& u) const {
;     ...
;         const long L = (long)i * G + c; if (L >= nwg) return false;
;         int wgid = (int)L; { const int q = nwg / NXCD, r = nwg % NXCD, xcd = wgid % NXCD, off = wgid / NXCD; wgid = (xcd < r ? xcd * (q + 1) : r * (q + 1) + (xcd - r) * q) + off; }
;         if (rev) wgid = nwg - 1 - wgid;
;         const int per = nM * nN, z = wgid / per, rem = wgid - z * per;
;         const int nig = WGM * nN, gid = rem / nig, fm = gid * WGM, gsz = (nM - fm) < WGM ? (nM - fm) : WGM, ri = rem - gid * nig;
;         u.pm = fm + (ri % gsz); u.pn = ri / gsz; u.z1 = z / Z2; u.z2 = z - u.z1 * Z2; return true;
; template <class Epi>
; __device__ __forceinline__ void gemm_phase(PG8_LAS unsigned char* lds, PG8_LAS unsigned char* xl, const Gemm g, const Sched& S, const Epi& E, const int wid) {
;     ...
;     if (!S.next(0, cur)) return;
.LBB0_752:
	v_readlane_b32 s8, v253, 0
	v_readlane_b32 s9, v253, 1
	v_readlane_b32 s0, v252, 41
	s_waitcnt lgkmcnt(0)
	s_barrier
	s_load_dwordx2 s[30:31], s[8:9], 0xd8
	v_readlane_b32 s4, v252, 46
	v_readlane_b32 s5, v252, 47
	s_mov_b32 s8, 8
	s_mov_b32 s9, 1
	s_movk_i32 s1, 0xa0
	s_and_b64 vcc, exec, s[4:5]
	v_mbcnt_lo_u32_b32 v8, -1, 0
	v_mbcnt_hi_u32_b32 v8, -1, v8
	s_cbranch_vccnz .LBB0_754
	s_mul_i32 s9, s1, s8
	s_abs_i32 s9, s9
	s_sub_i32 s10, 0, s9
	v_readlane_b32 s4, v254, 63
	s_nop 0
	s_mov_b32 s11, 0x333333
	s_mul_hi_u32 s10, s4, s11
	s_mul_i32 s10, s10, s9
	s_sub_i32 s10, s4, s10
	s_sub_i32 s11, s10, s9
	s_cmp_ge_u32 s10, s9
	s_cselect_b32 s10, s11, s10
	s_sub_i32 s11, s10, s9
	s_cmp_ge_u32 s10, s9
	s_cselect_b32 s9, s11, s10
	s_lshl_b32 s8, s8, 2
	s_abs_i32 s10, s8
	v_readlane_b32 s4, v254, 61
	s_sub_i32 s11, 0, s10
	s_xor_b32 s9, s9, s4
	s_sub_i32 s9, s9, s4
	s_abs_i32 s13, s9
	s_xor_b32 s12, s9, s8
	s_ashr_i32 s12, s12, 31
	s_mov_b32 s20, 0x8000000
	s_mul_hi_u32 s11, s13, s20
	s_mul_i32 s20, s11, s10
	s_sub_i32 s13, s13, s20
	s_add_i32 s21, s11, 1
	s_sub_i32 s20, s13, s10
	s_cmp_ge_u32 s13, s10
	s_cselect_b32 s11, s21, s11
	s_cselect_b32 s13, s20, s13
	s_add_i32 s20, s11, 1
	s_cmp_ge_u32 s13, s10
	s_cselect_b32 s10, s20, s11
	s_xor_b32 s10, s10, s12
	s_sub_i32 s10, s10, s12
	s_lshl_b32 s11, s10, 2
	s_sub_i32 s1, s1, s11
	s_min_i32 s1, s1, 4
	s_abs_i32 s12, s1
	s_sub_i32 s13, 0, s12
	s_mul_i32 s10, s10, s8
	s_sub_i32 s8, s9, s10
	s_abs_i32 s9, s8
	s_xor_b32 s10, s8, s1
	s_ashr_i32 s10, s10, 31
	s_mov_b32 s20, 0x40000000
	s_mul_hi_u32 s13, s9, s20
	s_mul_i32 s20, s13, s12
	s_sub_i32 s9, s9, s20
	s_add_i32 s21, s13, 1
	s_sub_i32 s20, s9, s12
	s_cmp_ge_u32 s9, s12
	s_cselect_b32 s13, s21, s13
	s_cselect_b32 s9, s20, s9
	s_add_i32 s20, s13, 1
	s_cmp_ge_u32 s9, s12
	s_cselect_b32 s9, s20, s13
	s_xor_b32 s9, s9, s10
	s_sub_i32 s12, s9, s10
	s_mul_i32 s1, s12, s1
	s_sub_i32 s1, s8, s1
	s_add_i32 s20, s11, s1

;     __device__ __forceinline__ bool next(int i, Unit& u) const {
;     ...
;         const long L = (long)i * G + c; if (L >= nwg) return false;
;         int wgid = (int)L; { const int q = nwg / NXCD, r = nwg % NXCD, xcd = wgid % NXCD, off = wgid / NXCD; wgid = (xcd < r ? xcd * (q + 1) : r * (q + 1) + (xcd - r) * q) + off; }
;         if (rev) wgid = nwg - 1 - wgid;
;         const int per = nM * nN, z = wgid / per, rem = wgid - z * per;
;         const int nig = WGM * nN, gid = rem / nig, fm = gid * WGM, gsz = (nM - fm) < WGM ? (nM - fm) : WGM, ri = rem - gid * nig;
;         u.pm = fm + (ri % gsz); u.pn = ri / gsz; u.z1 = z / Z2; u.z2 = z - u.z1 * Z2; return true;
.LBB0_760:
	s_mov_b32 s9, 8
	s_mov_b32 s10, 1
	s_movk_i32 s8, 0xa0
	s_add_i32 s69, s69, 1
	s_mul_i32 s10, s69, s68
	s_mul_hi_u32 s11, s69, s0
	s_add_i32 s11, s11, s10
	s_mul_i32 s10, s69, s0
	s_add_u32 s10, s10, s2
	s_addc_u32 s11, s11, s33
	v_cmp_gt_i64_e32 vcc, s[10:11], v[202:203]
	v_cmp_lt_i64_e64 s[48:49], s[10:11], v[200:201]
	s_cbranch_vccnz .LBB0_762
	s_ashr_i32 s11, s10, 31
	s_lshr_b32 s11, s11, 29
	s_add_i32 s11, s10, s11
	s_ashr_i32 s13, s11, 3
	s_and_b32 s11, s11, -8
	s_sub_i32 s10, s10, s11
	s_cmp_lt_i32 s10, 0
	s_movk_i32 s4, 0xa1
	s_mul_i32 s21, s8, s9
	s_cselect_b32 s11, s4, 0xa0
	s_abs_i32 s21, s21
	s_mul_i32 s10, s10, s11
	s_sub_i32 s11, 0, s21
	s_add_i32 s10, s10, s13
	s_ashr_i32 s13, s10, 31
	s_abs_i32 s10, s10
	s_mov_b32 s30, 0x333333
	s_mul_hi_u32 s11, s10, s30
	s_mul_i32 s11, s11, s21
	s_sub_i32 s10, s10, s11
	s_sub_i32 s11, s10, s21
	s_cmp_ge_u32 s10, s21
	s_cselect_b32 s10, s11, s10
	s_sub_i32 s11, s10, s21
	s_cmp_ge_u32 s10, s21
	s_cselect_b32 s10, s11, s10
	s_lshl_b32 s9, s9, 2
	s_abs_i32 s11, s9
	s_xor_b32 s10, s10, s13
	s_sub_i32 s10, s10, s13
	s_sub_i32 s13, 0, s11
	s_abs_i32 s30, s10
	s_xor_b32 s21, s10, s9
	s_ashr_i32 s21, s21, 31
	s_mov_b32 s31, 0x8000000
	s_mul_hi_u32 s13, s30, s31
	s_mul_i32 s31, s13, s11
	s_sub_i32 s30, s30, s31
	s_add_i32 s36, s13, 1
	s_sub_i32 s31, s30, s11
	s_cmp_ge_u32 s30, s11
	s_cselect_b32 s13, s36, s13
	s_cselect_b32 s30, s31, s30
	s_add_i32 s31, s13, 1
	s_cmp_ge_u32 s30, s11
	s_cselect_b32 s11, s31, s13
	s_xor_b32 s11, s11, s21
	s_sub_i32 s11, s11, s21
	s_lshl_b32 s13, s11, 2
	s_sub_i32 s8, s8, s13
	s_min_i32 s8, s8, 4
	s_abs_i32 s21, s8
	s_sub_i32 s30, 0, s21
	s_mul_i32 s11, s11, s9
	s_sub_i32 s9, s10, s11
	s_abs_i32 s10, s9
	s_xor_b32 s11, s9, s8
	s_ashr_i32 s11, s11, 31
	s_mov_b32 s31, 0x40000000
	s_mul_hi_u32 s30, s10, s31
	s_mul_i32 s31, s30, s21
	s_sub_i32 s10, s10, s31
	s_add_i32 s36, s30, 1
	s_sub_i32 s31, s10, s21
	s_cmp_ge_u32 s10, s21
	s_cselect_b32 s30, s36, s30
	s_cselect_b32 s10, s31, s10
	s_add_i32 s31, s30, 1
	s_cmp_ge_u32 s10, s21
	s_cselect_b32 s10, s31, s30
	s_xor_b32 s10, s10, s11
	s_sub_i32 s30, s10, s11
	s_mul_i32 s8, s30, s8
	s_sub_i32 s8, s9, s8
	s_add_i32 s70, s13, s8

;     __device__ __forceinline__ bool next(int i, Unit& u) const {
;     ...
;         const long L = (long)i * G + c; if (L >= nwg) return false;
;         int wgid = (int)L; { const int q = nwg / NXCD, r = nwg % NXCD, xcd = wgid % NXCD, off = wgid / NXCD; wgid = (xcd < r ? xcd * (q + 1) : r * (q + 1) + (xcd - r) * q) + off; }
;         if (rev) wgid = nwg - 1 - wgid;
;         const int per = nM * nN, z = wgid / per, rem = wgid - z * per;
;         const int nig = WGM * nN, gid = rem / nig, fm = gid * WGM, gsz = (nM - fm) < WGM ? (nM - fm) : WGM, ri = rem - gid * nig;
;         u.pm = fm + (ri % gsz); u.pn = ri / gsz; u.z1 = z / Z2; u.z2 = z - u.z1 * Z2; return true;
; template <class Epi>
; __device__ __forceinline__ void gemm_phase(PG8_LAS unsigned char* lds, PG8_LAS unsigned char* xl, const Gemm g, const Sched& S, const Epi& E, const int wid) {
;     ...
;     if (!S.next(0, cur)) return;
.LBB0_844:
	v_readlane_b32 s36, v253, 0
	v_readlane_b32 s37, v253, 1
	v_readlane_b32 s0, v252, 41
	s_waitcnt lgkmcnt(0)
	s_barrier
	s_load_dwordx2 s[30:31], s[36:37], 0xd8
	v_readlane_b32 s4, v252, 54
	v_readlane_b32 s5, v252, 55
	s_mov_b32 s8, 8
	s_mov_b32 s1, 1
	s_mov_b32 s9, 4
	s_and_b64 vcc, exec, s[4:5]
	v_mbcnt_lo_u32_b32 v8, -1, 0
	v_mbcnt_hi_u32_b32 v8, -1, v8
	s_cbranch_vccnz .LBB0_846
	s_mul_i32 s10, s8, s9
	s_abs_i32 s11, s10
	s_sub_i32 s13, 0, s11
	s_ashr_i32 s12, s10, 31
	v_readlane_b32 s4, v252, 0
	s_xor_b32 s12, s4, s12
	v_readlane_b32 s4, v252, 2
	s_mov_b32 s20, 0x8000000
	s_mul_hi_u32 s13, s4, s20
	s_mul_i32 s20, s13, s11
	s_sub_i32 s20, s4, s20
	s_add_i32 s21, s13, 1
	s_sub_i32 s40, s20, s11
	s_cmp_ge_u32 s20, s11
	s_cselect_b32 s13, s21, s13
	s_cselect_b32 s20, s40, s20
	s_add_i32 s21, s13, 1
	s_cmp_ge_u32 s20, s11
	s_cselect_b32 s11, s21, s13
	s_lshl_b32 s9, s9, 2
	s_abs_i32 s13, s9
	s_xor_b32 s11, s11, s12
	s_sub_i32 s11, s11, s12
	s_sub_i32 s12, 0, s13
	s_mul_i32 s10, s11, s10
	v_readlane_b32 s4, v252, 1
	s_sub_i32 s10, s4, s10
	s_abs_i32 s21, s10
	s_xor_b32 s20, s10, s9
	s_ashr_i32 s20, s20, 31
	s_mov_b32 s40, 0x10000000
	s_mul_hi_u32 s12, s21, s40
	s_mul_i32 s40, s12, s13
	s_sub_i32 s21, s21, s40
	s_add_i32 s41, s12, 1
	s_sub_i32 s40, s21, s13
	s_cmp_ge_u32 s21, s13
	s_cselect_b32 s12, s41, s12
	s_cselect_b32 s21, s40, s21
	s_add_i32 s40, s12, 1
	s_cmp_ge_u32 s21, s13
	s_cselect_b32 s12, s40, s12
	s_xor_b32 s12, s12, s20
	s_sub_i32 s12, s12, s20
	s_lshl_b32 s13, s12, 2
	s_sub_i32 s8, s8, s13
	s_min_i32 s8, s8, 4
	s_abs_i32 s20, s8
	s_sub_i32 s21, 0, s20
	s_mul_i32 s12, s12, s9
	s_sub_i32 s9, s10, s12
	s_abs_i32 s10, s9
	s_xor_b32 s12, s9, s8
	s_ashr_i32 s12, s12, 31
	s_mov_b32 s40, 0x40000000
	s_mul_hi_u32 s21, s10, s40
	s_mul_i32 s40, s21, s20
	s_sub_i32 s10, s10, s40
	s_add_i32 s41, s21, 1
	s_sub_i32 s40, s10, s20
	s_cmp_ge_u32 s10, s20
	s_cselect_b32 s21, s41, s21
	s_cselect_b32 s10, s40, s10
	s_add_i32 s40, s21, 1
	s_cmp_ge_u32 s10, s20
	s_cselect_b32 s10, s40, s21
	s_abs_i32 s20, s1
	s_xor_b32 s10, s10, s12
	s_sub_i32 s42, s10, s12
	s_mul_i32 s8, s42, s8
	s_sub_i32 s8, s9, s8
	s_sub_i32 s21, 0, s20
	s_add_i32 s52, s13, s8
	s_xor_b32 s1, s11, s1
	s_abs_i32 s11, s11
	s_ashr_i32 s1, s1, 31
	s_mov_b32 s8, 0xffffffff
	s_mul_i32 s21, s21, s8
	s_mul_hi_u32 s9, s8, s21
	s_add_i32 s8, s8, s9
	s_mul_hi_u32 s8, s11, s8
	s_mul_i32 s9, s8, s20
	s_sub_i32 s9, s11, s9
	s_add_i32 s10, s8, 1
	s_sub_i32 s11, s9, s20
	s_cmp_ge_u32 s9, s20
	s_cselect_b32 s8, s10, s8
	s_cselect_b32 s9, s11, s9
	s_add_i32 s10, s8, 1
	s_cmp_ge_u32 s9, s20
	s_cselect_b32 s8, s10, s8
	s_xor_b32 s8, s8, s1
	s_sub_i32 s56, s8, s1

;     __device__ __forceinline__ bool next(int i, Unit& u) const {
;     ...
;         const long L = (long)i * G + c; if (L >= nwg) return false;
;         int wgid = (int)L; { const int q = nwg / NXCD, r = nwg % NXCD, xcd = wgid % NXCD, off = wgid / NXCD; wgid = (xcd < r ? xcd * (q + 1) : r * (q + 1) + (xcd - r) * q) + off; }
;         if (rev) wgid = nwg - 1 - wgid;
;         const int per = nM * nN, z = wgid / per, rem = wgid - z * per;
;         const int nig = WGM * nN, gid = rem / nig, fm = gid * WGM, gsz = (nM - fm) < WGM ? (nM - fm) : WGM, ri = rem - gid * nig;
;         u.pm = fm + (ri % gsz); u.pn = ri / gsz; u.z1 = z / Z2; u.z2 = z - u.z1 * Z2; return true;
.LBB0_852:
	s_add_i32 s68, s68, 1
	s_mul_i32 s10, s68, s97
	s_mul_hi_u32 s11, s68, s0
	s_add_i32 s11, s11, s10
	s_mul_i32 s10, s68, s0
	s_add_u32 s10, s10, s2
	s_addc_u32 s11, s11, s33
	v_cmp_gt_i64_e32 vcc, s[10:11], v[198:199]
	s_mov_b32 s9, 8
	s_mov_b32 s8, 1
	s_mov_b32 s13, 4
	v_cmp_lt_i64_e64 s[46:47], s[10:11], v[196:197]
	s_cbranch_vccnz .LBB0_854
	s_ashr_i32 s11, s10, 31
	s_lshr_b32 s11, s11, 29
	s_add_i32 s11, s10, s11
	s_and_b32 s12, s11, -8
	s_sub_i32 s10, s10, s12
	s_ashr_i32 s11, s11, 3
	s_cmp_lt_i32 s10, 0
	s_mul_i32 s20, s9, s13
	s_cselect_b32 s12, s4, 0xffffffb0
	s_abs_i32 s21, s20
	s_mul_i32 s10, s10, s12
	s_sub_i32 s43, 0, s21
	s_sub_i32 s10, s10, s11
	s_addk_i32 s10, 0x27f
	s_abs_i32 s12, s10
	s_xor_b32 s11, s10, s20
	s_ashr_i32 s11, s11, 31
	s_mov_b32 s44, 0x8000000
	s_mul_hi_u32 s43, s12, s44
	s_mul_i32 s44, s43, s21
	s_sub_i32 s12, s12, s44
	s_add_i32 s44, s43, 1
	s_sub_i32 s45, s12, s21
	s_cmp_ge_u32 s12, s21
	s_cselect_b32 s43, s44, s43
	s_cselect_b32 s12, s45, s12
	s_add_i32 s44, s43, 1
	s_cmp_ge_u32 s12, s21
	s_cselect_b32 s12, s44, s43
	s_lshl_b32 s13, s13, 2
	s_abs_i32 s21, s13
	s_xor_b32 s12, s12, s11
	s_sub_i32 s11, s12, s11
	s_sub_i32 s43, 0, s21
	s_mul_i32 s12, s11, s20
	s_sub_i32 s10, s10, s12
	s_abs_i32 s20, s10
	s_xor_b32 s12, s10, s13
	s_ashr_i32 s12, s12, 31
	s_mov_b32 s44, 0x10000000
	s_mul_hi_u32 s43, s20, s44
	s_mul_i32 s44, s43, s21
	s_sub_i32 s20, s20, s44
	s_add_i32 s44, s43, 1
	s_sub_i32 s45, s20, s21
	s_cmp_ge_u32 s20, s21
	s_cselect_b32 s43, s44, s43
	s_cselect_b32 s20, s45, s20
	s_add_i32 s44, s43, 1
	s_cmp_ge_u32 s20, s21
	s_cselect_b32 s20, s44, s43
	s_xor_b32 s20, s20, s12
	s_sub_i32 s12, s20, s12
	s_lshl_b32 s20, s12, 2
	s_sub_i32 s9, s9, s20
	s_min_i32 s9, s9, 4
	s_abs_i32 s21, s9
	s_sub_i32 s43, 0, s21
	s_mul_i32 s12, s12, s13
	s_sub_i32 s10, s10, s12
	s_abs_i32 s13, s10
	s_xor_b32 s12, s10, s9
	s_ashr_i32 s12, s12, 31
	s_mov_b32 s44, 0x40000000
	s_mul_hi_u32 s43, s13, s44
	s_mul_i32 s44, s43, s21
	s_sub_i32 s13, s13, s44
	s_add_i32 s44, s43, 1
	s_sub_i32 s45, s13, s21
	s_cmp_ge_u32 s13, s21
	s_cselect_b32 s43, s44, s43
	s_cselect_b32 s13, s45, s13
	s_add_i32 s44, s43, 1
	s_cmp_ge_u32 s13, s21
	s_cselect_b32 s13, s44, s43
	s_abs_i32 s21, s8
	s_xor_b32 s13, s13, s12
	s_sub_i32 s12, s13, s12
	s_mul_i32 s9, s12, s9
	s_sub_i32 s9, s10, s9
	s_add_i32 s76, s20, s9
	s_xor_b32 s8, s11, s8
	s_abs_i32 s9, s11
	s_sub_i32 s10, 0, s21
	s_ashr_i32 s8, s8, 31
	s_mov_b32 s11, 0xffffffff
	s_mul_hi_u32 s10, s9, s11
	s_mul_i32 s11, s10, s21
	s_sub_i32 s9, s9, s11
	s_add_i32 s11, s10, 1
	s_sub_i32 s13, s9, s21
	s_cmp_ge_u32 s9, s21
	s_cselect_b32 s10, s11, s10
	s_cselect_b32 s9, s13, s9
	s_add_i32 s11, s10, 1
	s_cmp_ge_u32 s9, s21
	s_cselect_b32 s9, s11, s10
	s_xor_b32 s9, s9, s8
	s_sub_i32 s60, s9, s8

;     __device__ __forceinline__ bool next(int i, Unit& u) const {
;     ...
;         const long L = (long)i * G + c; if (L >= nwg) return false;
;         int wgid = (int)L; { const int q = nwg / NXCD, r = nwg % NXCD, xcd = wgid % NXCD, off = wgid / NXCD; wgid = (xcd < r ? xcd * (q + 1) : r * (q + 1) + (xcd - r) * q) + off; }
;         if (rev) wgid = nwg - 1 - wgid;
;         const int per = nM * nN, z = wgid / per, rem = wgid - z * per;
;         const int nig = WGM * nN, gid = rem / nig, fm = gid * WGM, gsz = (nM - fm) < WGM ? (nM - fm) : WGM, ri = rem - gid * nig;
;         u.pm = fm + (ri % gsz); u.pn = ri / gsz; u.z1 = z / Z2; u.z2 = z - u.z1 * Z2; return true;
; template <class Epi>
; __device__ __forceinline__ void gemm_phase(PG8_LAS unsigned char* lds, PG8_LAS unsigned char* xl, const Gemm g, const Sched& S, const Epi& E, const int wid) {
;     ...
;     if (!S.next(0, cur)) return;
.LBB0_944:
	v_readlane_b32 s8, v253, 0
	v_readlane_b32 s9, v253, 1
	v_readlane_b32 s0, v252, 41
	s_waitcnt lgkmcnt(0)
	s_barrier
	s_load_dwordx2 s[36:37], s[8:9], 0xd8
	v_readlane_b32 s4, v252, 46
	v_readlane_b32 s5, v252, 47
	s_mov_b32 s8, 8
	s_mov_b32 s9, 8
	s_mov_b32 s1, 1
	s_and_b64 vcc, exec, s[4:5]
	v_mbcnt_lo_u32_b32 v8, -1, 0
	v_mbcnt_hi_u32_b32 v8, -1, v8
	s_cbranch_vccnz .LBB0_946
	s_mul_i32 s10, s8, s9
	s_abs_i32 s11, s10
	s_sub_i32 s13, 0, s11
	s_ashr_i32 s12, s10, 31
	v_readlane_b32 s4, v254, 61
	s_xor_b32 s12, s4, s12
	v_readlane_b32 s4, v254, 63
	s_mov_b32 s20, 0x4000000
	s_mul_hi_u32 s13, s4, s20
	s_mul_i32 s20, s13, s11
	s_sub_i32 s20, s4, s20
	s_add_i32 s21, s13, 1
	s_sub_i32 s30, s20, s11
	s_cmp_ge_u32 s20, s11
	s_cselect_b32 s13, s21, s13
	s_cselect_b32 s20, s30, s20
	s_add_i32 s21, s13, 1
	s_cmp_ge_u32 s20, s11
	s_cselect_b32 s11, s21, s13
	s_lshl_b32 s9, s9, 2
	s_abs_i32 s13, s9
	s_xor_b32 s11, s11, s12
	s_sub_i32 s11, s11, s12
	s_sub_i32 s12, 0, s13
	s_mul_i32 s10, s11, s10
	v_readlane_b32 s4, v254, 62
	s_sub_i32 s10, s4, s10
	s_abs_i32 s21, s10
	s_xor_b32 s20, s10, s9
	s_ashr_i32 s20, s20, 31
	s_mov_b32 s30, 0x8000000
	s_mul_hi_u32 s12, s21, s30
	s_mul_i32 s30, s12, s13
	s_sub_i32 s21, s21, s30
	s_add_i32 s31, s12, 1
	s_sub_i32 s30, s21, s13
	s_cmp_ge_u32 s21, s13
	s_cselect_b32 s12, s31, s12
	s_cselect_b32 s21, s30, s21
	s_add_i32 s30, s12, 1
	s_cmp_ge_u32 s21, s13
	s_cselect_b32 s12, s30, s12
	s_xor_b32 s12, s12, s20
	s_sub_i32 s12, s12, s20
	s_lshl_b32 s13, s12, 2
	s_sub_i32 s8, s8, s13
	s_min_i32 s8, s8, 4
	s_abs_i32 s20, s8
	s_sub_i32 s21, 0, s20
	s_mul_i32 s12, s12, s9
	s_sub_i32 s9, s10, s12
	s_abs_i32 s10, s9
	s_xor_b32 s12, s9, s8
	s_ashr_i32 s12, s12, 31
	s_mov_b32 s30, 0x40000000
	s_mul_hi_u32 s21, s10, s30
	s_mul_i32 s30, s21, s20
	s_sub_i32 s10, s10, s30
	s_add_i32 s31, s21, 1
	s_sub_i32 s30, s10, s20
	s_cmp_ge_u32 s10, s20
	s_cselect_b32 s21, s31, s21
	s_cselect_b32 s10, s30, s10
	s_add_i32 s30, s21, 1
	s_cmp_ge_u32 s10, s20
	s_cselect_b32 s10, s30, s21
	s_abs_i32 s21, s1
	s_xor_b32 s10, s10, s12
	s_sub_i32 s12, s10, s12
	s_mul_i32 s8, s12, s8
	s_sub_i32 s8, s9, s8
	s_sub_i32 s30, 0, s21
	s_add_i32 s20, s13, s8
	s_xor_b32 s1, s11, s1
	s_abs_i32 s11, s11
	s_ashr_i32 s1, s1, 31
	s_mov_b32 s8, 0xffffffff
	s_mul_i32 s30, s30, s8
	s_mul_hi_u32 s9, s8, s30
	s_add_i32 s8, s8, s9
	s_mul_hi_u32 s8, s11, s8
	s_mul_i32 s9, s8, s21
	s_sub_i32 s9, s11, s9
	s_add_i32 s10, s8, 1
	s_sub_i32 s11, s9, s21
	s_cmp_ge_u32 s9, s21
	s_cselect_b32 s8, s10, s8
	s_cselect_b32 s9, s11, s9
	s_add_i32 s10, s8, 1
	s_cmp_ge_u32 s9, s21
	s_cselect_b32 s8, s10, s8
	s_xor_b32 s8, s8, s1
	s_sub_i32 s30, s8, s1

;     __device__ __forceinline__ bool next(int i, Unit& u) const {
;     ...
;         const long L = (long)i * G + c; if (L >= nwg) return false;
;         int wgid = (int)L; { const int q = nwg / NXCD, r = nwg % NXCD, xcd = wgid % NXCD, off = wgid / NXCD; wgid = (xcd < r ? xcd * (q + 1) : r * (q + 1) + (xcd - r) * q) + off; }
;         if (rev) wgid = nwg - 1 - wgid;
;         const int per = nM * nN, z = wgid / per, rem = wgid - z * per;
;         const int nig = WGM * nN, gid = rem / nig, fm = gid * WGM, gsz = (nM - fm) < WGM ? (nM - fm) : WGM, ri = rem - gid * nig;
;         u.pm = fm + (ri % gsz); u.pn = ri / gsz; u.z1 = z / Z2; u.z2 = z - u.z1 * Z2; return true;
.LBB0_952:
	s_add_i32 s90, s90, 1
	s_mul_i32 s10, s90, s89
	s_mul_hi_u32 s11, s90, s0
	s_add_i32 s11, s11, s10
	s_mul_i32 s10, s90, s0
	s_add_u32 s10, s10, s2
	s_addc_u32 s11, s11, s33
	v_cmp_gt_i64_e32 vcc, s[10:11], v[202:203]
	s_mov_b32 s9, 8
	s_mov_b32 s13, 8
	s_mov_b32 s8, 1
	v_cmp_lt_i64_e64 s[46:47], s[10:11], v[200:201]
	s_cbranch_vccnz .LBB0_954
	s_ashr_i32 s11, s10, 31
	s_lshr_b32 s11, s11, 29
	s_add_i32 s11, s10, s11
	s_ashr_i32 s21, s11, 3
	s_and_b32 s11, s11, -8
	s_sub_i32 s10, s10, s11
	s_cmp_lt_i32 s10, 0
	s_movk_i32 s4, 0xa1
	s_mul_i32 s31, s9, s13
	s_cselect_b32 s11, s4, 0xa0
	s_abs_i32 s36, s31
	s_mul_i32 s10, s10, s11
	s_sub_i32 s11, 0, s36
	s_add_i32 s10, s10, s21
	s_abs_i32 s37, s10
	s_xor_b32 s21, s10, s31
	s_ashr_i32 s21, s21, 31
	s_mov_b32 s42, 0x4000000
	s_mul_hi_u32 s11, s37, s42
	s_mul_i32 s42, s11, s36
	s_sub_i32 s37, s37, s42
	s_add_i32 s42, s11, 1
	s_sub_i32 s43, s37, s36
	s_cmp_ge_u32 s37, s36
	s_cselect_b32 s11, s42, s11
	s_cselect_b32 s37, s43, s37
	s_add_i32 s42, s11, 1
	s_cmp_ge_u32 s37, s36
	s_cselect_b32 s11, s42, s11
	s_lshl_b32 s13, s13, 2
	s_abs_i32 s36, s13
	s_xor_b32 s11, s11, s21
	s_sub_i32 s11, s11, s21
	s_sub_i32 s37, 0, s36
	s_mul_i32 s21, s11, s31
	s_sub_i32 s10, s10, s21
	s_abs_i32 s31, s10
	s_xor_b32 s21, s10, s13
	s_ashr_i32 s21, s21, 31
	s_mov_b32 s42, 0x8000000
	s_mul_hi_u32 s37, s31, s42
	s_mul_i32 s42, s37, s36
	s_sub_i32 s31, s31, s42
	s_add_i32 s42, s37, 1
	s_sub_i32 s43, s31, s36
	s_cmp_ge_u32 s31, s36
	s_cselect_b32 s37, s42, s37
	s_cselect_b32 s31, s43, s31
	s_add_i32 s42, s37, 1
	s_cmp_ge_u32 s31, s36
	s_cselect_b32 s31, s42, s37
	s_xor_b32 s31, s31, s21
	s_sub_i32 s21, s31, s21
	s_lshl_b32 s31, s21, 2
	s_sub_i32 s9, s9, s31
	s_min_i32 s9, s9, 4
	s_abs_i32 s36, s9
	s_sub_i32 s37, 0, s36
	s_mul_i32 s21, s21, s13
	s_sub_i32 s10, s10, s21
	s_abs_i32 s21, s10
	s_xor_b32 s13, s10, s9
	s_ashr_i32 s13, s13, 31
	s_mov_b32 s42, 0x40000000
	s_mul_hi_u32 s37, s21, s42
	s_mul_i32 s42, s37, s36
	s_sub_i32 s21, s21, s42
	s_add_i32 s42, s37, 1
	s_sub_i32 s43, s21, s36
	s_cmp_ge_u32 s21, s36
	s_cselect_b32 s37, s42, s37
	s_cselect_b32 s21, s43, s21
	s_add_i32 s42, s37, 1
	s_cmp_ge_u32 s21, s36
	s_cselect_b32 s21, s42, s37
	s_abs_i32 s37, s8
	s_xor_b32 s21, s21, s13
	s_sub_i32 s36, s21, s13
	s_mul_i32 s9, s36, s9
	s_sub_i32 s9, s10, s9
	s_add_i32 s42, s31, s9
	s_xor_b32 s8, s11, s8
	s_abs_i32 s9, s11
	s_sub_i32 s10, 0, s37
	s_ashr_i32 s8, s8, 31
	s_mov_b32 s11, 0xffffffff
	s_mul_hi_u32 s10, s9, s11
	s_mul_i32 s11, s10, s37
	s_sub_i32 s9, s9, s11
	s_add_i32 s11, s10, 1
	s_sub_i32 s13, s9, s37
	s_cmp_ge_u32 s9, s37
	s_cselect_b32 s10, s11, s10
	s_cselect_b32 s9, s13, s9
	s_add_i32 s11, s10, 1
	s_cmp_ge_u32 s9, s37
	s_cselect_b32 s9, s11, s10
	s_xor_b32 s9, s9, s8
	s_sub_i32 s48, s9, s8

;     __device__ __forceinline__ bool next(int i, Unit& u) const {
;     ...
;         const long L = (long)i * G + c; if (L >= nwg) return false;
;         int wgid = (int)L; { const int q = nwg / NXCD, r = nwg % NXCD, xcd = wgid % NXCD, off = wgid / NXCD; wgid = (xcd < r ? xcd * (q + 1) : r * (q + 1) + (xcd - r) * q) + off; }
;         if (rev) wgid = nwg - 1 - wgid;
;         const int per = nM * nN, z = wgid / per, rem = wgid - z * per;
;         const int nig = WGM * nN, gid = rem / nig, fm = gid * WGM, gsz = (nM - fm) < WGM ? (nM - fm) : WGM, ri = rem - gid * nig;
;         u.pm = fm + (ri % gsz); u.pn = ri / gsz; u.z1 = z / Z2; u.z2 = z - u.z1 * Z2; return true;
; template <class Epi>
; __device__ __forceinline__ void gemm_phase(PG8_LAS unsigned char* lds, PG8_LAS unsigned char* xl, const Gemm g, const Sched& S, const Epi& E, const int wid) {
;     ...
;     if (!S.next(0, cur)) return;
.LBB0_1095:
	v_readlane_b32 s36, v253, 0
	v_readlane_b32 s37, v253, 1
	s_waitcnt lgkmcnt(0)
	s_barrier
	v_readlane_b32 s68, v252, 41
	s_load_dwordx4 s[48:51], s[36:37], 0xb0
	s_load_dwordx2 s[20:21], s[36:37], 0xd8
	v_readlane_b32 s4, v254, 40
	v_readlane_b32 s5, v254, 41
	s_mov_b32 s8, 1
	s_mov_b32 s1, 44
	v_cndmask_b32_e64 v0, 0, 1, s[4:5]
	s_movk_i32 s0, 0xa0
	v_cmp_ne_u32_e64 s[44:45], 1, v0
	s_andn2_b64 vcc, exec, s[4:5]
	v_mbcnt_lo_u32_b32 v12, -1, 0
	v_mbcnt_hi_u32_b32 v12, -1, v12
	s_cbranch_vccnz .LBB0_1097
	s_mul_i32 s8, s0, s1
	s_abs_i32 s8, s8
	s_sub_i32 s9, 0, s8
	v_readlane_b32 s4, v254, 55
	s_nop 0
	s_mov_b32 s10, 0x94f20
	s_mul_hi_u32 s9, s4, s10
	s_mul_i32 s9, s9, s8
	s_sub_i32 s9, s4, s9
	s_sub_i32 s10, s9, s8
	s_cmp_ge_u32 s9, s8
	s_cselect_b32 s9, s10, s9
	s_sub_i32 s10, s9, s8
	s_cmp_ge_u32 s9, s8
	s_cselect_b32 s8, s10, s9
	s_lshl_b32 s1, s1, 2
	s_abs_i32 s9, s1
	v_readlane_b32 s4, v254, 54
	s_sub_i32 s10, 0, s9
	s_xor_b32 s8, s8, s4
	s_sub_i32 s8, s8, s4
	s_abs_i32 s12, s8
	s_xor_b32 s11, s8, s1
	s_ashr_i32 s11, s11, 31
	s_mov_b32 s13, 0x1745d17
	s_mul_hi_u32 s10, s12, s13
	s_mul_i32 s13, s10, s9
	s_sub_i32 s12, s12, s13
	s_add_i32 s30, s10, 1
	s_sub_i32 s13, s12, s9
	s_cmp_ge_u32 s12, s9
	s_cselect_b32 s10, s30, s10
	s_cselect_b32 s12, s13, s12
	s_add_i32 s13, s10, 1
	s_cmp_ge_u32 s12, s9
	s_cselect_b32 s9, s13, s10
	s_xor_b32 s9, s9, s11
	s_sub_i32 s9, s9, s11
	s_lshl_b32 s10, s9, 2
	s_sub_i32 s0, s0, s10
	s_min_i32 s0, s0, 4
	s_abs_i32 s11, s0
	s_sub_i32 s12, 0, s11
	s_mul_i32 s9, s9, s1
	s_sub_i32 s1, s8, s9
	s_abs_i32 s8, s1
	s_xor_b32 s9, s1, s0
	s_ashr_i32 s9, s9, 31
	s_mov_b32 s13, 0x40000000
	s_mul_hi_u32 s12, s8, s13
	s_mul_i32 s13, s12, s11
	s_sub_i32 s8, s8, s13
	s_add_i32 s30, s12, 1
	s_sub_i32 s13, s8, s11
	s_cmp_ge_u32 s8, s11
	s_cselect_b32 s12, s30, s12
	s_cselect_b32 s8, s13, s8
	s_add_i32 s13, s12, 1
	s_cmp_ge_u32 s8, s11
	s_cselect_b32 s8, s13, s12
	s_xor_b32 s8, s8, s9
	s_sub_i32 s60, s8, s9
	s_mul_i32 s0, s60, s0
	s_sub_i32 s0, s1, s0
	s_add_i32 s12, s10, s0

;     __device__ __forceinline__ bool next(int i, Unit& u) const {
;     ...
;         const long L = (long)i * G + c; if (L >= nwg) return false;
;         int wgid = (int)L; { const int q = nwg / NXCD, r = nwg % NXCD, xcd = wgid % NXCD, off = wgid / NXCD; wgid = (xcd < r ? xcd * (q + 1) : r * (q + 1) + (xcd - r) * q) + off; }
;         if (rev) wgid = nwg - 1 - wgid;
;         const int per = nM * nN, z = wgid / per, rem = wgid - z * per;
;         const int nig = WGM * nN, gid = rem / nig, fm = gid * WGM, gsz = (nM - fm) < WGM ? (nM - fm) : WGM, ri = rem - gid * nig;
;         u.pm = fm + (ri % gsz); u.pn = ri / gsz; u.z1 = z / Z2; u.z2 = z - u.z1 * Z2; return true;
.LBB0_1103:
	s_mov_b32 s10, 1
	s_mov_b32 s9, 44
	s_movk_i32 s8, 0xa0
	s_add_i32 s67, s67, 1
	s_mul_i32 s10, s67, s66
	s_mul_hi_u32 s11, s67, s68
	s_add_i32 s11, s11, s10
	s_mul_i32 s10, s67, s68
	s_add_u32 s10, s10, s2
	s_addc_u32 s11, s11, s33
	v_cmp_gt_i64_e32 vcc, s[10:11], v[208:209]
	v_cmp_lt_i64_e64 s[46:47], s[10:11], v[206:207]
	s_cbranch_vccnz .LBB0_1105
	s_ashr_i32 s11, s10, 31
	s_lshr_b32 s11, s11, 29
	s_add_i32 s11, s10, s11
	s_and_b32 s48, s11, -8
	s_sub_i32 s10, s10, s48
	s_ashr_i32 s11, s11, 3
	s_cmp_lt_i32 s10, 0
	s_movk_i32 s4, 0xfc8f
	s_mul_i32 s49, s8, s9
	s_cselect_b32 s48, s4, 0xfffffc90
	s_abs_i32 s49, s49
	s_mul_i32 s10, s10, s48
	s_sub_i32 s48, 0, s49
	s_sub_i32 s10, s10, s11
	s_addk_i32 s10, 0x1b7f
	s_ashr_i32 s11, s10, 31
	s_abs_i32 s10, s10
	s_mov_b32 s50, 0x94f20
	s_mul_hi_u32 s48, s10, s50
	s_mul_i32 s48, s48, s49
	s_sub_i32 s10, s10, s48
	s_sub_i32 s48, s10, s49
	s_cmp_ge_u32 s10, s49
	s_cselect_b32 s10, s48, s10
	s_sub_i32 s48, s10, s49
	s_cmp_ge_u32 s10, s49
	s_cselect_b32 s10, s48, s10
	s_lshl_b32 s9, s9, 2
	s_abs_i32 s48, s9
	s_xor_b32 s10, s10, s11
	s_sub_i32 s10, s10, s11
	s_sub_i32 s11, 0, s48
	s_abs_i32 s50, s10
	s_xor_b32 s49, s10, s9
	s_ashr_i32 s49, s49, 31
	s_mov_b32 s51, 0x1745d17
	s_mul_hi_u32 s11, s50, s51
	s_mul_i32 s51, s11, s48
	s_sub_i32 s50, s50, s51
	s_add_i32 s54, s11, 1
	s_sub_i32 s51, s50, s48
	s_cmp_ge_u32 s50, s48
	s_cselect_b32 s11, s54, s11
	s_cselect_b32 s50, s51, s50
	s_add_i32 s51, s11, 1
	s_cmp_ge_u32 s50, s48
	s_cselect_b32 s11, s51, s11
	s_xor_b32 s11, s11, s49
	s_sub_i32 s11, s11, s49
	s_lshl_b32 s49, s11, 2
	s_sub_i32 s8, s8, s49
	s_min_i32 s8, s8, 4
	s_abs_i32 s48, s8
	s_sub_i32 s50, 0, s48
	s_mul_i32 s11, s11, s9
	s_sub_i32 s9, s10, s11
	s_abs_i32 s10, s9
	s_xor_b32 s11, s9, s8
	s_ashr_i32 s11, s11, 31
	s_mov_b32 s51, 0x40000000
	s_mul_hi_u32 s50, s10, s51
	s_mul_i32 s51, s50, s48
	s_sub_i32 s10, s10, s51
	s_add_i32 s54, s50, 1
	s_sub_i32 s51, s10, s48
	s_cmp_ge_u32 s10, s48
	s_cselect_b32 s50, s54, s50
	s_cselect_b32 s10, s51, s10
	s_add_i32 s51, s50, 1
	s_cmp_ge_u32 s10, s48
	s_cselect_b32 s10, s51, s50
	s_xor_b32 s10, s10, s11
	s_sub_i32 s48, s10, s11
	s_mul_i32 s8, s48, s8
	s_sub_i32 s8, s9, s8
	s_add_i32 s50, s49, s8

;     __device__ __forceinline__ bool next(int i, Unit& u) const {
;     ...
;         const long L = (long)i * G + c; if (L >= nwg) return false;
;         int wgid = (int)L; { const int q = nwg / NXCD, r = nwg % NXCD, xcd = wgid % NXCD, off = wgid / NXCD; wgid = (xcd < r ? xcd * (q + 1) : r * (q + 1) + (xcd - r) * q) + off; }
;         if (rev) wgid = nwg - 1 - wgid;
;         const int per = nM * nN, z = wgid / per, rem = wgid - z * per;
;         const int nig = WGM * nN, gid = rem / nig, fm = gid * WGM, gsz = (nM - fm) < WGM ? (nM - fm) : WGM, ri = rem - gid * nig;
;         u.pm = fm + (ri % gsz); u.pn = ri / gsz; u.z1 = z / Z2; u.z2 = z - u.z1 * Z2; return true;
; template <class Epi>
; __device__ __forceinline__ void gemm_phase(PG8_LAS unsigned char* lds, PG8_LAS unsigned char* xl, const Gemm g, const Sched& S, const Epi& E, const int wid) {
;     ...
;     if (!S.next(0, cur)) return;
.LBB0_1289:
	v_readlane_b32 s0, v253, 0
	v_readlane_b32 s1, v253, 1
	v_readlane_b32 s46, v252, 41
	s_waitcnt lgkmcnt(0)
	s_barrier
	s_load_dwordx2 s[20:21], s[0:1], 0xd8
	v_readlane_b32 s4, v252, 46
	s_mov_b32 s8, 8
	s_mov_b32 s0, 1
	s_movk_i32 s1, 0xa0
	v_readlane_b32 s5, v252, 47
	v_mbcnt_lo_u32_b32 v8, -1, 0
	v_mbcnt_hi_u32_b32 v8, -1, v8
	s_and_b64 vcc, exec, s[4:5]
	s_cbranch_vccnz .LBB0_1291
	s_mul_i32 s0, s1, s8
	s_abs_i32 s0, s0
	s_sub_i32 s4, 0, s0
	v_readlane_b32 s9, v254, 63
	s_nop 0
	s_mov_b32 s5, 0x333333
	s_mul_hi_u32 s4, s9, s5
	s_mul_i32 s4, s4, s0
	s_sub_i32 s4, s9, s4
	s_sub_i32 s5, s4, s0
	s_cmp_ge_u32 s4, s0
	s_cselect_b32 s4, s5, s4
	s_sub_i32 s5, s4, s0
	s_cmp_ge_u32 s4, s0
	s_cselect_b32 s0, s5, s4
	s_lshl_b32 s4, s8, 2
	s_abs_i32 s5, s4
	v_readlane_b32 s8, v254, 61
	s_xor_b32 s0, s0, s8
	s_sub_i32 s0, s0, s8
	s_sub_i32 s8, 0, s5
	s_abs_i32 s10, s0
	s_xor_b32 s9, s0, s4
	s_ashr_i32 s9, s9, 31
	s_mov_b32 s11, 0x8000000
	s_mul_hi_u32 s8, s10, s11
	s_mul_i32 s11, s8, s5
	s_sub_i32 s10, s10, s11
	s_add_i32 s12, s8, 1
	s_sub_i32 s11, s10, s5
	s_cmp_ge_u32 s10, s5
	s_cselect_b32 s8, s12, s8
	s_cselect_b32 s10, s11, s10
	s_add_i32 s11, s8, 1
	s_cmp_ge_u32 s10, s5
	s_cselect_b32 s5, s11, s8
	s_xor_b32 s5, s5, s9
	s_sub_i32 s5, s5, s9
	s_lshl_b32 s8, s5, 2
	s_sub_i32 s1, s1, s8
	s_min_i32 s1, s1, 4
	s_abs_i32 s9, s1
	s_sub_i32 s10, 0, s9
	s_mul_i32 s5, s5, s4
	s_sub_i32 s4, s0, s5
	s_abs_i32 s0, s4
	s_xor_b32 s5, s4, s1
	s_ashr_i32 s5, s5, 31
	s_mov_b32 s11, 0x40000000
	s_mul_hi_u32 s10, s0, s11
	s_mul_i32 s11, s10, s9
	s_sub_i32 s0, s0, s11
	s_add_i32 s12, s10, 1
	s_sub_i32 s11, s0, s9
	s_cmp_ge_u32 s0, s9
	s_cselect_b32 s10, s12, s10
	s_cselect_b32 s0, s11, s0
	s_add_i32 s11, s10, 1
	s_cmp_ge_u32 s0, s9
	s_cselect_b32 s0, s11, s10
	s_xor_b32 s0, s0, s5
	s_sub_i32 s0, s0, s5
	s_mul_i32 s1, s0, s1
	s_sub_i32 s1, s4, s1
	s_add_i32 s12, s8, s1

;     __device__ __forceinline__ bool next(int i, Unit& u) const {
;     ...
;         const long L = (long)i * G + c; if (L >= nwg) return false;
;         int wgid = (int)L; { const int q = nwg / NXCD, r = nwg % NXCD, xcd = wgid % NXCD, off = wgid / NXCD; wgid = (xcd < r ? xcd * (q + 1) : r * (q + 1) + (xcd - r) * q) + off; }
;         if (rev) wgid = nwg - 1 - wgid;
;         const int per = nM * nN, z = wgid / per, rem = wgid - z * per;
;         const int nig = WGM * nN, gid = rem / nig, fm = gid * WGM, gsz = (nM - fm) < WGM ? (nM - fm) : WGM, ri = rem - gid * nig;
;         u.pm = fm + (ri % gsz); u.pn = ri / gsz; u.z1 = z / Z2; u.z2 = z - u.z1 * Z2; return true;
.LBB0_1297:
	s_mov_b32 s8, 8
	s_mov_b32 s4, 1
	s_movk_i32 s1, 0xa0
	s_add_i32 s67, s67, 1
	s_mul_i32 s4, s67, s66
	s_mul_hi_u32 s5, s67, s46
	s_add_i32 s5, s5, s4
	s_mul_i32 s4, s67, s46
	s_add_u32 s10, s4, s2
	s_addc_u32 s11, s5, s33
	v_cmp_gt_i64_e32 vcc, s[10:11], v[202:203]
	v_cmp_lt_i64_e64 s[44:45], s[10:11], v[200:201]
	s_cbranch_vccnz .LBB0_1299
	s_ashr_i32 s4, s10, 31
	s_lshr_b32 s4, s4, 29
	s_add_i32 s4, s10, s4
	s_ashr_i32 s5, s4, 3
	s_and_b32 s4, s4, -8
	s_sub_i32 s4, s10, s4
	s_cmp_lt_i32 s4, 0
	s_movk_i32 s9, 0xa1
	s_mul_i32 s10, s1, s8
	s_cselect_b32 s9, s9, 0xa0
	s_abs_i32 s10, s10
	s_mul_i32 s4, s4, s9
	s_sub_i32 s9, 0, s10
	s_add_i32 s4, s4, s5
	s_ashr_i32 s5, s4, 31
	s_abs_i32 s4, s4
	s_mov_b32 s11, 0x333333
	s_mul_hi_u32 s9, s4, s11
	s_mul_i32 s9, s9, s10
	s_sub_i32 s4, s4, s9
	s_sub_i32 s9, s4, s10
	s_cmp_ge_u32 s4, s10
	s_cselect_b32 s4, s9, s4
	s_sub_i32 s9, s4, s10
	s_cmp_ge_u32 s4, s10
	s_cselect_b32 s4, s9, s4
	s_lshl_b32 s8, s8, 2
	s_abs_i32 s9, s8
	s_xor_b32 s4, s4, s5
	s_sub_i32 s4, s4, s5
	s_sub_i32 s5, 0, s9
	s_abs_i32 s11, s4
	s_xor_b32 s10, s4, s8
	s_ashr_i32 s10, s10, 31
	s_mov_b32 s13, 0x8000000
	s_mul_hi_u32 s5, s11, s13
	s_mul_i32 s13, s5, s9
	s_sub_i32 s11, s11, s13
	s_add_i32 s20, s5, 1
	s_sub_i32 s13, s11, s9
	s_cmp_ge_u32 s11, s9
	s_cselect_b32 s5, s20, s5
	s_cselect_b32 s11, s13, s11
	s_add_i32 s13, s5, 1
	s_cmp_ge_u32 s11, s9
	s_cselect_b32 s5, s13, s5
	s_xor_b32 s5, s5, s10
	s_sub_i32 s5, s5, s10
	s_lshl_b32 s9, s5, 2
	s_sub_i32 s1, s1, s9
	s_min_i32 s1, s1, 4
	s_abs_i32 s10, s1
	s_sub_i32 s11, 0, s10
	s_mul_i32 s5, s5, s8
	s_sub_i32 s4, s4, s5
	s_abs_i32 s5, s4
	s_xor_b32 s8, s4, s1
	s_ashr_i32 s8, s8, 31
	s_mov_b32 s13, 0x40000000
	s_mul_hi_u32 s11, s5, s13
	s_mul_i32 s13, s11, s10
	s_sub_i32 s5, s5, s13
	s_add_i32 s20, s11, 1
	s_sub_i32 s13, s5, s10
	s_cmp_ge_u32 s5, s10
	s_cselect_b32 s11, s20, s11
	s_cselect_b32 s5, s13, s5
	s_add_i32 s13, s11, 1
	s_cmp_ge_u32 s5, s10
	s_cselect_b32 s5, s13, s11
	s_xor_b32 s5, s5, s8
	s_sub_i32 s68, s5, s8
	s_mul_i32 s1, s68, s1
	s_sub_i32 s1, s4, s1
	s_add_i32 s69, s9, s1
